# x2 stores of the w_out phase (and its fix-up) without the nt hint so the FFN2-down epilogue's residual reads can hit the memory-side cache
# speedup vs baseline: 1.0081x; 1.0081x over previous
;     __device__ __forceinline__ void operator()(const f32x4 (&acc)[2][2][4][2], const Unit& u, int wr, int wc, int fr, int fq) const {
;     ...
;         const int row0 = u.pm * BM + wr * 64 + fr, col0 = u.pn * BM + wc * 32 + 8 * fq;
;         f32x4 gv[2][2];
; #pragma unroll
;         for (int bj = 0; bj < 2; ++bj)
; #pragma unroll
;             for (int n = 0; n < 2; ++n) gv[bj][n] = An ? *(const f32x4*)(gn + col0 + bj * HALF + 4 * n) : (f32x4){0.f, 0.f, 0.f, 0.f};
;         const float* bb = (u.pm * BM < TP) ? base0 : base1 - (size_t)TP * D;
; #pragma unroll
;         for (int ai = 0; ai < 2; ++ai) {
;             if (quad >= 0 && (quad >> 1) != ai) continue;
;             f32x4 rr[4][2][2];
; #pragma unroll
;             for (int m = 0; m < 4; ++m)
; #pragma unroll
;                 for (int bj = 0; bj < 2; ++bj) { const size_t off = (size_t)(row0 + ai * HALF + m * 16) * D + col0 + bj * HALF;
;                     if (quad >= 0 && (quad & 1) != bj) { rr[m][bj][0] = (f32x4){0.f, 0.f, 0.f, 0.f}; rr[m][bj][1] = rr[m][bj][0]; }
;                     else { rr[m][bj][0] = *(const f32x4*)(bb + off); rr[m][bj][1] = *(const f32x4*)(bb + off + 4); } }
;             __builtin_amdgcn_sched_barrier(0);
; #pragma unroll
;             for (int m = 0; m < 4; ++m) {
;                 const int row = row0 + ai * HALF + m * 16; const size_t off = (size_t)row * D + col0;
;                 float q = 0.f;
; #pragma unroll
;                 for (int bj = 0; bj < 2; ++bj) {
;                     if (quad >= 0 && (quad & 1) != bj) continue;
;                     const f32x4 v0 = rr[m][bj][0] + acc[ai][bj][m][0] * scale, v1 = rr[m][bj][1] + acc[ai][bj][m][1] * scale;
;                     q += dot4(v0) + dot4(v1);
;                     __builtin_nontemporal_store(v0, (f32x4*)(out + off + bj * HALF)); __builtin_nontemporal_store(v1, (f32x4*)(out + off + bj * HALF + 4));
;                     if (An) { const f32x4 a0 = v0 * gv[bj][0], a1 = v1 * gv[bj][1]; u32x4 w; w.x = pk2(a0[0], a0[1]); w.y = pk2(a0[2], a0[3]); w.z = pk2(a1[0], a1[1]); w.w = pk2(a1[2], a1[3]);
;                         *(u32x4*)(An + off + bj * HALF) = w; }
;                 }
;                 q += __shfl_xor(q, 16); q += __shfl_xor(q, 32);
;                 if (fq == 0) __hip_atomic_fetch_add(ss + row, q, __ATOMIC_RELAXED, __HIP_MEMORY_SCOPE_AGENT);
.LBB0_986:
	v_lshl_or_b32 v204, s77, 8, v193
	v_ashrrev_i32_e32 v205, 31, v204
	v_lshl_add_u32 v208, s58, 8, v223
	v_lshlrev_b64 v[144:145], 2, v[204:205]
	v_ashrrev_i32_e32 v209, 31, v208
	v_or_b32_e32 v218, 16, v208
	v_lshl_add_u64 v[132:133], s[22:23], 0, v[144:145]
	v_lshl_add_u64 v[206:207], s[12:13], 0, v[144:145]
	v_lshlrev_b64 v[144:145], 13, v[208:209]
	v_ashrrev_i32_e32 v219, 31, v218
	v_or_b32_e32 v214, 32, v208
	v_lshl_add_u64 v[242:243], v[206:207], 0, v[144:145]
	v_lshlrev_b64 v[144:145], 13, v[218:219]
	v_ashrrev_i32_e32 v215, 31, v214
	v_or_b32_e32 v210, 48, v208
	v_lshl_add_u64 v[220:221], v[206:207], 0, v[144:145]
	v_lshlrev_b64 v[144:145], 13, v[214:215]
	v_ashrrev_i32_e32 v211, 31, v210
	v_lshl_add_u64 v[216:217], v[206:207], 0, v[144:145]
	v_lshlrev_b64 v[144:145], 13, v[210:211]
	v_lshl_add_u64 v[212:213], v[206:207], 0, v[144:145]
	global_load_dwordx4 v[136:139], v[132:133], off offset:16
	global_load_dwordx4 v[140:143], v[132:133], off
	global_load_dwordx4 v[128:131], v[132:133], off offset:528
	s_nop 0
	global_load_dwordx4 v[132:135], v[132:133], off offset:512
	s_nop 0
	global_load_dwordx4 v[226:229], v[242:243], off offset:16
	global_load_dwordx4 v[230:233], v[242:243], off
	global_load_dwordx4 v[234:237], v[242:243], off offset:528
	global_load_dwordx4 v[238:241], v[242:243], off offset:512
	global_load_dwordx4 v[184:187], v[220:221], off offset:16
	global_load_dwordx4 v[188:191], v[220:221], off
	global_load_dwordx4 v[176:179], v[220:221], off offset:528
	global_load_dwordx4 v[180:183], v[220:221], off offset:512
	global_load_dwordx4 v[168:171], v[216:217], off offset:16
	global_load_dwordx4 v[172:175], v[216:217], off
	global_load_dwordx4 v[160:163], v[216:217], off offset:528
	global_load_dwordx4 v[164:167], v[216:217], off offset:512
	global_load_dwordx4 v[152:155], v[212:213], off offset:16
	global_load_dwordx4 v[156:159], v[212:213], off
	global_load_dwordx4 v[144:147], v[212:213], off offset:528
	global_load_dwordx4 v[148:151], v[212:213], off offset:512
	s_waitcnt vmcnt(0)
	v_pk_add_f32 v[232:233], v[232:233], v[126:127]
	v_pk_add_f32 v[230:231], v[230:231], v[124:125]
	v_mul_f32_e32 v247, v233, v233
	v_mul_f32_e32 v246, v231, v231
	v_pk_add_f32 v[228:229], v[228:229], v[122:123]
	v_pk_add_f32 v[226:227], v[226:227], v[120:121]
	v_fmac_f32_e32 v246, v230, v230
	v_fmac_f32_e32 v247, v232, v232
	v_add_f32_e32 v246, v246, v247
	v_mul_f32_e32 v247, v227, v227
	v_mul_f32_e32 v248, v229, v229
	v_fmac_f32_e32 v247, v226, v226
	v_fmac_f32_e32 v248, v228, v228
	v_lshlrev_b64 v[244:245], 11, v[208:209]
	v_add_f32_e32 v247, v247, v248
	v_lshl_add_u64 v[244:245], v[244:245], 0, v[204:205]
	v_add_f32_e32 v248, v246, v247
	global_store_dwordx4 v[242:243], v[230:233], off
	global_store_dwordx4 v[242:243], v[226:229], off offset:16
	v_pk_mul_f32 v[246:247], v[138:139], v[228:229]
	v_pk_mul_f32 v[232:233], v[142:143], v[232:233]
	v_pk_mul_f32 v[228:229], v[136:137], v[226:227]
	v_pk_mul_f32 v[230:231], v[140:141], v[230:231]
	v_lshl_add_u64 v[244:245], v[244:245], 1, s[46:47]
	v_cvt_pk_bf16_f32 v226, v230, v231
	v_cvt_pk_bf16_f32 v227, v232, v233
	v_cvt_pk_bf16_f32 v228, v228, v229
	v_cvt_pk_bf16_f32 v229, v246, v247
	global_store_dwordx4 v[244:245], v[226:229], off
	v_pk_add_f32 v[230:231], v[240:241], v[94:95]
	v_pk_add_f32 v[236:237], v[236:237], v[90:91]
	v_pk_add_f32 v[228:229], v[238:239], v[92:93]
	v_mul_f32_e32 v227, v231, v231
	v_mul_f32_e32 v226, v229, v229
	v_pk_add_f32 v[234:235], v[234:235], v[88:89]
	v_fmac_f32_e32 v226, v228, v228
	v_fmac_f32_e32 v227, v230, v230
	v_add_f32_e32 v226, v226, v227
	v_mul_f32_e32 v227, v235, v235
	v_mul_f32_e32 v232, v237, v237
	v_fmac_f32_e32 v227, v234, v234
	v_fmac_f32_e32 v232, v236, v236
	v_add_f32_e32 v227, v227, v232
	v_add_f32_e32 v226, v226, v227
	global_store_dwordx4 v[242:243], v[228:231], off offset:512
	global_store_dwordx4 v[242:243], v[234:237], off offset:528
	v_pk_mul_f32 v[232:233], v[134:135], v[230:231]
	v_and_b32_e32 v230, 64, v225
	v_add_f32_e32 v227, v248, v226
	v_xor_b32_e32 v226, 16, v225
	v_add_u32_e32 v231, 64, v230
	v_cmp_lt_i32_e32 vcc, v226, v231
	v_pk_mul_f32 v[228:229], v[132:133], v[228:229]
	v_pk_mul_f32 v[236:237], v[130:131], v[236:237]
	v_cndmask_b32_e32 v226, v225, v226, vcc
	v_lshlrev_b32_e32 v226, 2, v226
	ds_bpermute_b32 v238, v226, v227
	v_cvt_pk_bf16_f32 v230, v228, v229
	v_pk_mul_f32 v[234:235], v[128:129], v[234:235]
	s_waitcnt lgkmcnt(0)
	v_add_f32_e32 v228, v227, v238
	v_xor_b32_e32 v227, 32, v225
	v_cmp_lt_i32_e32 vcc, v227, v231
	v_cvt_pk_bf16_f32 v231, v232, v233
	v_cvt_pk_bf16_f32 v232, v234, v235
	v_cvt_pk_bf16_f32 v233, v236, v237
	global_store_dwordx4 v[244:245], v[230:233], off offset:256
	s_nop 0
	v_cndmask_b32_e32 v227, v225, v227, vcc
	v_lshlrev_b32_e32 v227, 2, v227
	ds_bpermute_b32 v229, v227, v228
	s_and_saveexec_b64 s[34:35], s[8:9]
	s_cbranch_execz .LBB0_988
	s_waitcnt lgkmcnt(0)
	v_add_f32_e32 v230, v228, v229
	v_lshl_add_u64 v[228:229], v[208:209], 2, s[48:49]
	global_atomic_add_f32 v[228:229], v230, off
; __device__ __forceinline__ unsigned pk2(float lo, float hi) { unsigned r; asm volatile("v_cvt_pk_bf16_f32 %0, %1, %2" : "=v"(r) : "v"(lo), "v"(hi)); return r; }
; __device__ __forceinline__ float dot4(f32x4 v) { return (v[0] * v[0] + v[1] * v[1]) + (v[2] * v[2] + v[3] * v[3]); }
;     __device__ __forceinline__ void operator()(const f32x4 (&acc)[2][2][4][2], const Unit& u, int wr, int wc, int fr, int fq) const {
;     ...
;             for (int m = 0; m < 4; ++m) {
;                 const int row = row0 + ai * HALF + m * 16; const size_t off = (size_t)row * D + col0;
;                 float q = 0.f;
; #pragma unroll
;                 for (int bj = 0; bj < 2; ++bj) {
;                     if (quad >= 0 && (quad & 1) != bj) continue;
;                     const f32x4 v0 = rr[m][bj][0] + acc[ai][bj][m][0] * scale, v1 = rr[m][bj][1] + acc[ai][bj][m][1] * scale;
;                     q += dot4(v0) + dot4(v1);
;                     __builtin_nontemporal_store(v0, (f32x4*)(out + off + bj * HALF)); __builtin_nontemporal_store(v1, (f32x4*)(out + off + bj * HALF + 4));
;                     if (An) { const f32x4 a0 = v0 * gv[bj][0], a1 = v1 * gv[bj][1]; u32x4 w; w.x = pk2(a0[0], a0[1]); w.y = pk2(a0[2], a0[3]); w.z = pk2(a1[0], a1[1]); w.w = pk2(a1[2], a1[3]);
;                         *(u32x4*)(An + off + bj * HALF) = w; }
;                 }
;                 q += __shfl_xor(q, 16); q += __shfl_xor(q, 32);
;                 if (fq == 0) __hip_atomic_fetch_add(ss + row, q, __ATOMIC_RELAXED, __HIP_MEMORY_SCOPE_AGENT);
.LBB0_988:
	s_or_b64 exec, exec, s[34:35]
	v_pk_add_f32 v[190:191], v[190:191], v[118:119]
	v_pk_add_f32 v[188:189], v[188:189], v[116:117]
	v_mul_f32_e32 v230, v191, v191
	v_mul_f32_e32 v209, v189, v189
	v_pk_add_f32 v[186:187], v[186:187], v[114:115]
	v_pk_add_f32 v[184:185], v[184:185], v[112:113]
	v_fmac_f32_e32 v209, v188, v188
	v_fmac_f32_e32 v230, v190, v190
	v_add_f32_e32 v209, v209, v230
	v_mul_f32_e32 v230, v185, v185
	v_mul_f32_e32 v231, v187, v187
	s_waitcnt lgkmcnt(0)
	v_lshlrev_b64 v[228:229], 11, v[218:219]
	v_fmac_f32_e32 v230, v184, v184
	v_fmac_f32_e32 v231, v186, v186
	v_lshl_add_u64 v[228:229], v[228:229], 0, v[204:205]
	v_add_f32_e32 v230, v230, v231
	global_store_dwordx4 v[220:221], v[188:191], off
	global_store_dwordx4 v[220:221], v[184:187], off offset:16
	v_add_f32_e32 v209, v209, v230
	v_pk_mul_f32 v[188:189], v[140:141], v[188:189]
	v_pk_mul_f32 v[190:191], v[142:143], v[190:191]
	v_pk_mul_f32 v[230:231], v[138:139], v[186:187]
	v_pk_mul_f32 v[186:187], v[136:137], v[184:185]
	v_cvt_pk_bf16_f32 v184, v188, v189
	v_cvt_pk_bf16_f32 v185, v190, v191
	v_lshl_add_u64 v[188:189], v[228:229], 1, s[46:47]
	v_pk_add_f32 v[182:183], v[182:183], v[86:87]
	v_pk_add_f32 v[180:181], v[180:181], v[84:85]
	v_cvt_pk_bf16_f32 v186, v186, v187
	v_cvt_pk_bf16_f32 v187, v230, v231
	global_store_dwordx4 v[188:189], v[184:187], off
	v_pk_add_f32 v[178:179], v[178:179], v[82:83]
	v_pk_add_f32 v[176:177], v[176:177], v[80:81]
	v_mul_f32_e32 v184, v181, v181
	v_mul_f32_e32 v185, v183, v183
	v_fmac_f32_e32 v184, v180, v180
	v_fmac_f32_e32 v185, v182, v182
	v_add_f32_e32 v184, v184, v185
	v_mul_f32_e32 v185, v177, v177
	v_mul_f32_e32 v186, v179, v179
	v_fmac_f32_e32 v185, v176, v176
	v_fmac_f32_e32 v186, v178, v178
	v_add_f32_e32 v185, v185, v186
	v_add_f32_e32 v184, v184, v185
	v_add_f32_e32 v190, v209, v184
	ds_bpermute_b32 v191, v226, v190
	global_store_dwordx4 v[220:221], v[180:183], off offset:512
	global_store_dwordx4 v[220:221], v[176:179], off offset:528
	v_pk_mul_f32 v[186:187], v[128:129], v[176:177]
	v_pk_mul_f32 v[180:181], v[132:133], v[180:181]
	v_pk_mul_f32 v[182:183], v[134:135], v[182:183]
	s_waitcnt lgkmcnt(0)
	v_add_f32_e32 v176, v190, v191
	ds_bpermute_b32 v177, v227, v176
	v_pk_mul_f32 v[184:185], v[130:131], v[178:179]
	v_cvt_pk_bf16_f32 v178, v180, v181
	v_cvt_pk_bf16_f32 v179, v182, v183
	v_cvt_pk_bf16_f32 v180, v186, v187
	s_nop 0
	v_cvt_pk_bf16_f32 v181, v184, v185
	global_store_dwordx4 v[188:189], v[178:181], off offset:256
	s_and_saveexec_b64 s[34:35], s[8:9]
	s_cbranch_execz .LBB0_990
	s_waitcnt lgkmcnt(0)
	v_add_f32_e32 v178, v176, v177
	v_lshl_add_u64 v[176:177], v[218:219], 2, s[48:49]
	global_atomic_add_f32 v[176:177], v178, off
.LBB0_990:
	s_or_b64 exec, exec, s[34:35]
	v_pk_add_f32 v[174:175], v[174:175], v[110:111]
	v_pk_add_f32 v[172:173], v[172:173], v[108:109]
	v_mul_f32_e32 v179, v175, v175
	v_mul_f32_e32 v178, v173, v173
	v_pk_add_f32 v[170:171], v[170:171], v[106:107]
	v_pk_add_f32 v[168:169], v[168:169], v[104:105]
	v_fmac_f32_e32 v178, v172, v172
	v_fmac_f32_e32 v179, v174, v174
	v_add_f32_e32 v178, v178, v179
	v_mul_f32_e32 v179, v169, v169
	v_mul_f32_e32 v180, v171, v171
	s_waitcnt lgkmcnt(0)
	v_lshlrev_b64 v[176:177], 11, v[214:215]
	v_fmac_f32_e32 v179, v168, v168
	v_fmac_f32_e32 v180, v170, v170
	v_lshl_add_u64 v[176:177], v[176:177], 0, v[204:205]
	v_add_f32_e32 v179, v179, v180
	global_store_dwordx4 v[216:217], v[172:175], off
	global_store_dwordx4 v[216:217], v[168:171], off offset:16
	v_add_f32_e32 v180, v178, v179
	v_pk_mul_f32 v[172:173], v[140:141], v[172:173]
	v_pk_mul_f32 v[174:175], v[142:143], v[174:175]
	v_pk_mul_f32 v[178:179], v[138:139], v[170:171]
	v_pk_mul_f32 v[170:171], v[136:137], v[168:169]
	v_cvt_pk_bf16_f32 v168, v172, v173
	v_cvt_pk_bf16_f32 v169, v174, v175
	v_lshl_add_u64 v[172:173], v[176:177], 1, s[46:47]
	v_pk_add_f32 v[166:167], v[166:167], v[78:79]
	v_pk_add_f32 v[164:165], v[164:165], v[76:77]
	v_cvt_pk_bf16_f32 v170, v170, v171
	v_cvt_pk_bf16_f32 v171, v178, v179
	global_store_dwordx4 v[172:173], v[168:171], off
	v_pk_add_f32 v[162:163], v[162:163], v[74:75]
	v_pk_add_f32 v[160:161], v[160:161], v[72:73]
	v_mul_f32_e32 v168, v165, v165
	v_mul_f32_e32 v169, v167, v167
	v_fmac_f32_e32 v168, v164, v164
	v_fmac_f32_e32 v169, v166, v166
	v_add_f32_e32 v168, v168, v169
	v_mul_f32_e32 v169, v161, v161
	v_mul_f32_e32 v170, v163, v163
	v_fmac_f32_e32 v169, v160, v160
	v_fmac_f32_e32 v170, v162, v162
	v_add_f32_e32 v169, v169, v170
	v_add_f32_e32 v168, v168, v169
	v_add_f32_e32 v174, v180, v168
	ds_bpermute_b32 v175, v226, v174
	global_store_dwordx4 v[216:217], v[164:167], off offset:512
	global_store_dwordx4 v[216:217], v[160:163], off offset:528
	v_pk_mul_f32 v[170:171], v[128:129], v[160:161]
	v_pk_mul_f32 v[164:165], v[132:133], v[164:165]
	v_pk_mul_f32 v[166:167], v[134:135], v[166:167]
	s_waitcnt lgkmcnt(0)
	v_add_f32_e32 v160, v174, v175
	ds_bpermute_b32 v161, v227, v160
	v_pk_mul_f32 v[168:169], v[130:131], v[162:163]
	v_cvt_pk_bf16_f32 v162, v164, v165
	v_cvt_pk_bf16_f32 v163, v166, v167
	v_cvt_pk_bf16_f32 v164, v170, v171
	s_nop 0
	v_cvt_pk_bf16_f32 v165, v168, v169
	global_store_dwordx4 v[172:173], v[162:165], off offset:256
	s_and_saveexec_b64 s[34:35], s[8:9]
	s_cbranch_execz .LBB0_992
	s_waitcnt lgkmcnt(0)
	v_add_f32_e32 v162, v160, v161
	v_lshl_add_u64 v[160:161], v[214:215], 2, s[48:49]
	global_atomic_add_f32 v[160:161], v162, off
; __device__ __forceinline__ unsigned pk2(float lo, float hi) { unsigned r; asm volatile("v_cvt_pk_bf16_f32 %0, %1, %2" : "=v"(r) : "v"(lo), "v"(hi)); return r; }
; __device__ __forceinline__ float dot4(f32x4 v) { return (v[0] * v[0] + v[1] * v[1]) + (v[2] * v[2] + v[3] * v[3]); }
;     __device__ __forceinline__ void operator()(const f32x4 (&acc)[2][2][4][2], const Unit& u, int wr, int wc, int fr, int fq) const {
;     ...
;             for (int m = 0; m < 4; ++m)
; #pragma unroll
;                 for (int bj = 0; bj < 2; ++bj) { const size_t off = (size_t)(row0 + ai * HALF + m * 16) * D + col0 + bj * HALF;
;                     if (quad >= 0 && (quad & 1) != bj) { rr[m][bj][0] = (f32x4){0.f, 0.f, 0.f, 0.f}; rr[m][bj][1] = rr[m][bj][0]; }
;                     else { rr[m][bj][0] = *(const f32x4*)(bb + off); rr[m][bj][1] = *(const f32x4*)(bb + off + 4); } }
;             __builtin_amdgcn_sched_barrier(0);
; #pragma unroll
;             for (int m = 0; m < 4; ++m) {
;                 const int row = row0 + ai * HALF + m * 16; const size_t off = (size_t)row * D + col0;
;                 float q = 0.f;
; #pragma unroll
;                 for (int bj = 0; bj < 2; ++bj) {
;                     if (quad >= 0 && (quad & 1) != bj) continue;
;                     const f32x4 v0 = rr[m][bj][0] + acc[ai][bj][m][0] * scale, v1 = rr[m][bj][1] + acc[ai][bj][m][1] * scale;
;                     q += dot4(v0) + dot4(v1);
;                     __builtin_nontemporal_store(v0, (f32x4*)(out + off + bj * HALF)); __builtin_nontemporal_store(v1, (f32x4*)(out + off + bj * HALF + 4));
;                     if (An) { const f32x4 a0 = v0 * gv[bj][0], a1 = v1 * gv[bj][1]; u32x4 w; w.x = pk2(a0[0], a0[1]); w.y = pk2(a0[2], a0[3]); w.z = pk2(a1[0], a1[1]); w.w = pk2(a1[2], a1[3]);
;                         *(u32x4*)(An + off + bj * HALF) = w; }
;                 }
;                 q += __shfl_xor(q, 16); q += __shfl_xor(q, 32);
;                 if (fq == 0) __hip_atomic_fetch_add(ss + row, q, __ATOMIC_RELAXED, __HIP_MEMORY_SCOPE_AGENT);
.LBB0_992:
	s_or_b64 exec, exec, s[34:35]
	v_pk_add_f32 v[158:159], v[158:159], v[102:103]
	v_pk_add_f32 v[156:157], v[156:157], v[100:101]
	v_mul_f32_e32 v163, v159, v159
	v_mul_f32_e32 v162, v157, v157
	v_pk_add_f32 v[154:155], v[154:155], v[98:99]
	v_pk_add_f32 v[152:153], v[152:153], v[96:97]
	v_fmac_f32_e32 v162, v156, v156
	v_fmac_f32_e32 v163, v158, v158
	v_add_f32_e32 v162, v162, v163
	v_mul_f32_e32 v163, v153, v153
	v_mul_f32_e32 v164, v155, v155
	s_waitcnt lgkmcnt(0)
	v_lshlrev_b64 v[160:161], 11, v[210:211]
	v_fmac_f32_e32 v163, v152, v152
	v_fmac_f32_e32 v164, v154, v154
	v_lshl_add_u64 v[160:161], v[160:161], 0, v[204:205]
	v_add_f32_e32 v163, v163, v164
	global_store_dwordx4 v[212:213], v[156:159], off
	global_store_dwordx4 v[212:213], v[152:155], off offset:16
	v_add_f32_e32 v164, v162, v163
	v_pk_mul_f32 v[156:157], v[140:141], v[156:157]
	v_pk_mul_f32 v[158:159], v[142:143], v[158:159]
	v_pk_mul_f32 v[162:163], v[138:139], v[154:155]
	v_pk_mul_f32 v[154:155], v[136:137], v[152:153]
	v_cvt_pk_bf16_f32 v152, v156, v157
	v_cvt_pk_bf16_f32 v153, v158, v159
	v_lshl_add_u64 v[156:157], v[160:161], 1, s[46:47]
	v_pk_add_f32 v[150:151], v[150:151], v[70:71]
	v_pk_add_f32 v[148:149], v[148:149], v[68:69]
	v_cvt_pk_bf16_f32 v154, v154, v155
	v_cvt_pk_bf16_f32 v155, v162, v163
	global_store_dwordx4 v[156:157], v[152:155], off
	v_pk_add_f32 v[146:147], v[146:147], v[66:67]
	v_pk_add_f32 v[144:145], v[144:145], v[64:65]
	v_mul_f32_e32 v152, v149, v149
	v_mul_f32_e32 v153, v151, v151
	v_fmac_f32_e32 v152, v148, v148
	v_fmac_f32_e32 v153, v150, v150
	v_add_f32_e32 v152, v152, v153
	v_mul_f32_e32 v153, v145, v145
	v_mul_f32_e32 v154, v147, v147
	v_fmac_f32_e32 v153, v144, v144
	v_fmac_f32_e32 v154, v146, v146
	v_add_f32_e32 v153, v153, v154
	v_add_f32_e32 v152, v152, v153
	v_add_f32_e32 v158, v164, v152
	ds_bpermute_b32 v159, v226, v158
	global_store_dwordx4 v[212:213], v[148:151], off offset:512
	global_store_dwordx4 v[212:213], v[144:147], off offset:528
	v_pk_mul_f32 v[154:155], v[128:129], v[144:145]
	v_pk_mul_f32 v[148:149], v[132:133], v[148:149]
	v_pk_mul_f32 v[150:151], v[134:135], v[150:151]
	s_waitcnt lgkmcnt(0)
	v_add_f32_e32 v144, v158, v159
	ds_bpermute_b32 v145, v227, v144
	v_pk_mul_f32 v[152:153], v[130:131], v[146:147]
	v_cvt_pk_bf16_f32 v146, v148, v149
	v_cvt_pk_bf16_f32 v147, v150, v151
	v_cvt_pk_bf16_f32 v148, v154, v155
	s_nop 0
	v_cvt_pk_bf16_f32 v149, v152, v153
	global_store_dwordx4 v[156:157], v[146:149], off offset:256
	s_and_saveexec_b64 s[34:35], s[8:9]
	s_cbranch_execz .LBB0_994
	s_waitcnt lgkmcnt(0)
	v_add_f32_e32 v146, v144, v145
	v_lshl_add_u64 v[144:145], v[210:211], 2, s[48:49]
	global_atomic_add_f32 v[144:145], v146, off
.LBB0_994:
	s_or_b64 exec, exec, s[34:35]
	v_add_u32_e32 v218, 0x80, v208
	v_ashrrev_i32_e32 v219, 31, v218
	v_add_u32_e32 v214, 0x90, v208
	s_waitcnt lgkmcnt(0)
	v_lshlrev_b64 v[144:145], 13, v[218:219]
	v_ashrrev_i32_e32 v215, 31, v214
	v_add_u32_e32 v210, 0xa0, v208
	v_lshl_add_u64 v[220:221], v[206:207], 0, v[144:145]
	v_lshlrev_b64 v[144:145], 13, v[214:215]
	v_ashrrev_i32_e32 v211, 31, v210
	v_add_u32_e32 v208, 0xb0, v208
	v_lshl_add_u64 v[216:217], v[206:207], 0, v[144:145]
	v_lshlrev_b64 v[144:145], 13, v[210:211]
	v_ashrrev_i32_e32 v209, 31, v208
	v_lshl_add_u64 v[212:213], v[206:207], 0, v[144:145]
	v_lshlrev_b64 v[144:145], 13, v[208:209]
	v_lshl_add_u64 v[206:207], v[206:207], 0, v[144:145]
	global_load_dwordx4 v[228:231], v[220:221], off offset:16
	global_load_dwordx4 v[232:235], v[220:221], off
	global_load_dwordx4 v[236:239], v[220:221], off offset:528
	global_load_dwordx4 v[240:243], v[220:221], off offset:512
	global_load_dwordx4 v[184:187], v[216:217], off offset:16
	global_load_dwordx4 v[188:191], v[216:217], off
	global_load_dwordx4 v[176:179], v[216:217], off offset:528
	global_load_dwordx4 v[180:183], v[216:217], off offset:512
	global_load_dwordx4 v[168:171], v[212:213], off offset:16
	global_load_dwordx4 v[172:175], v[212:213], off
	global_load_dwordx4 v[160:163], v[212:213], off offset:528
	global_load_dwordx4 v[164:167], v[212:213], off offset:512
	global_load_dwordx4 v[152:155], v[206:207], off offset:16
	global_load_dwordx4 v[156:159], v[206:207], off
	global_load_dwordx4 v[144:147], v[206:207], off offset:528
	global_load_dwordx4 v[148:151], v[206:207], off offset:512
	s_waitcnt vmcnt(14)
	v_pk_add_f32 v[234:235], v[62:63], v[234:235]
	v_pk_add_f32 v[232:233], v[60:61], v[232:233]
	v_mul_f32_e32 v247, v235, v235
	v_mul_f32_e32 v246, v233, v233
	v_pk_add_f32 v[230:231], v[58:59], v[230:231]
	v_pk_add_f32 v[228:229], v[56:57], v[228:229]
	v_fmac_f32_e32 v246, v232, v232
	v_fmac_f32_e32 v247, v234, v234
	v_add_f32_e32 v246, v246, v247
	v_mul_f32_e32 v247, v229, v229
	v_mul_f32_e32 v248, v231, v231
	v_fmac_f32_e32 v247, v228, v228
	v_fmac_f32_e32 v248, v230, v230
	v_lshlrev_b64 v[244:245], 11, v[218:219]
	v_add_f32_e32 v247, v247, v248
	v_lshl_add_u64 v[244:245], v[244:245], 0, v[204:205]
	v_add_f32_e32 v248, v246, v247
	global_store_dwordx4 v[220:221], v[232:235], off
	global_store_dwordx4 v[220:221], v[228:231], off offset:16
	v_pk_mul_f32 v[246:247], v[138:139], v[230:231]
	v_pk_mul_f32 v[234:235], v[142:143], v[234:235]
	v_pk_mul_f32 v[230:231], v[136:137], v[228:229]
	v_pk_mul_f32 v[232:233], v[140:141], v[232:233]
	v_lshl_add_u64 v[244:245], v[244:245], 1, s[46:47]
	v_cvt_pk_bf16_f32 v228, v232, v233
	v_cvt_pk_bf16_f32 v229, v234, v235
	v_cvt_pk_bf16_f32 v230, v230, v231
	v_cvt_pk_bf16_f32 v231, v246, v247
	global_store_dwordx4 v[244:245], v[228:231], off
	s_waitcnt vmcnt(16)
	v_pk_add_f32 v[232:233], v[24:25], v[236:237]
	v_pk_add_f32 v[234:235], v[26:27], v[238:239]
	s_waitcnt vmcnt(15)
	v_pk_add_f32 v[230:231], v[30:31], v[242:243]
	v_pk_add_f32 v[228:229], v[28:29], v[240:241]
	v_mul_f32_e32 v237, v231, v231
	v_mul_f32_e32 v236, v229, v229
	v_fmac_f32_e32 v236, v228, v228
	v_fmac_f32_e32 v237, v230, v230
	v_add_f32_e32 v236, v236, v237
	v_mul_f32_e32 v237, v233, v233
	v_mul_f32_e32 v238, v235, v235
	v_fmac_f32_e32 v237, v232, v232
	v_fmac_f32_e32 v238, v234, v234
	v_add_f32_e32 v237, v237, v238
	v_add_f32_e32 v236, v236, v237
	v_add_f32_e32 v236, v248, v236
	ds_bpermute_b32 v237, v226, v236
	global_store_dwordx4 v[220:221], v[228:231], off offset:512
	global_store_dwordx4 v[220:221], v[232:235], off offset:528
	v_pk_mul_f32 v[220:221], v[132:133], v[228:229]
	v_pk_mul_f32 v[230:231], v[134:135], v[230:231]
	v_cvt_pk_bf16_f32 v228, v220, v221
	s_waitcnt lgkmcnt(0)
	v_add_f32_e32 v220, v236, v237
	ds_bpermute_b32 v221, v227, v220
	v_pk_mul_f32 v[234:235], v[130:131], v[234:235]
	v_pk_mul_f32 v[232:233], v[128:129], v[232:233]
	v_cvt_pk_bf16_f32 v229, v230, v231
	s_nop 0
	v_cvt_pk_bf16_f32 v230, v232, v233
	v_cvt_pk_bf16_f32 v231, v234, v235
	global_store_dwordx4 v[244:245], v[228:231], off offset:256
	s_and_saveexec_b64 s[34:35], s[8:9]
	s_cbranch_execz .LBB0_996
	s_waitcnt lgkmcnt(0)
	v_add_f32_e32 v220, v220, v221
	v_lshl_add_u64 v[218:219], v[218:219], 2, s[48:49]
	global_atomic_add_f32 v[218:219], v220, off
; __device__ __forceinline__ unsigned pk2(float lo, float hi) { unsigned r; asm volatile("v_cvt_pk_bf16_f32 %0, %1, %2" : "=v"(r) : "v"(lo), "v"(hi)); return r; }
; __device__ __forceinline__ float dot4(f32x4 v) { return (v[0] * v[0] + v[1] * v[1]) + (v[2] * v[2] + v[3] * v[3]); }
;     __device__ __forceinline__ void operator()(const f32x4 (&acc)[2][2][4][2], const Unit& u, int wr, int wc, int fr, int fq) const {
;     ...
;             for (int m = 0; m < 4; ++m) {
;                 const int row = row0 + ai * HALF + m * 16; const size_t off = (size_t)row * D + col0;
;                 float q = 0.f;
; #pragma unroll
;                 for (int bj = 0; bj < 2; ++bj) {
;                     if (quad >= 0 && (quad & 1) != bj) continue;
;                     const f32x4 v0 = rr[m][bj][0] + acc[ai][bj][m][0] * scale, v1 = rr[m][bj][1] + acc[ai][bj][m][1] * scale;
;                     q += dot4(v0) + dot4(v1);
;                     __builtin_nontemporal_store(v0, (f32x4*)(out + off + bj * HALF)); __builtin_nontemporal_store(v1, (f32x4*)(out + off + bj * HALF + 4));
;                     if (An) { const f32x4 a0 = v0 * gv[bj][0], a1 = v1 * gv[bj][1]; u32x4 w; w.x = pk2(a0[0], a0[1]); w.y = pk2(a0[2], a0[3]); w.z = pk2(a1[0], a1[1]); w.w = pk2(a1[2], a1[3]);
;                         *(u32x4*)(An + off + bj * HALF) = w; }
;                 }
;                 q += __shfl_xor(q, 16); q += __shfl_xor(q, 32);
;                 if (fq == 0) __hip_atomic_fetch_add(ss + row, q, __ATOMIC_RELAXED, __HIP_MEMORY_SCOPE_AGENT);
.LBB0_996:
	s_or_b64 exec, exec, s[34:35]
	s_waitcnt vmcnt(16)
	v_pk_add_f32 v[190:191], v[54:55], v[190:191]
	v_pk_add_f32 v[188:189], v[52:53], v[188:189]
	s_waitcnt lgkmcnt(0)
	v_mul_f32_e32 v221, v191, v191
	v_mul_f32_e32 v220, v189, v189
	v_pk_add_f32 v[186:187], v[50:51], v[186:187]
	v_pk_add_f32 v[184:185], v[48:49], v[184:185]
	v_fmac_f32_e32 v220, v188, v188
	v_fmac_f32_e32 v221, v190, v190
	v_add_f32_e32 v220, v220, v221
	v_mul_f32_e32 v221, v185, v185
	v_mul_f32_e32 v228, v187, v187
	v_lshlrev_b64 v[218:219], 11, v[214:215]
	v_fmac_f32_e32 v221, v184, v184
	v_fmac_f32_e32 v228, v186, v186
	v_lshl_add_u64 v[218:219], v[218:219], 0, v[204:205]
	v_add_f32_e32 v221, v221, v228
	global_store_dwordx4 v[216:217], v[188:191], off
	global_store_dwordx4 v[216:217], v[184:187], off offset:16
	v_add_f32_e32 v228, v220, v221
	v_pk_mul_f32 v[188:189], v[140:141], v[188:189]
	v_pk_mul_f32 v[190:191], v[142:143], v[190:191]
	v_pk_mul_f32 v[220:221], v[138:139], v[186:187]
	v_pk_mul_f32 v[186:187], v[136:137], v[184:185]
	v_cvt_pk_bf16_f32 v184, v188, v189
	v_cvt_pk_bf16_f32 v185, v190, v191
	v_lshl_add_u64 v[188:189], v[218:219], 1, s[46:47]
	s_waitcnt vmcnt(16)
	v_pk_add_f32 v[182:183], v[22:23], v[182:183]
	v_pk_add_f32 v[180:181], v[20:21], v[180:181]
	v_cvt_pk_bf16_f32 v186, v186, v187
	v_cvt_pk_bf16_f32 v187, v220, v221
	global_store_dwordx4 v[188:189], v[184:187], off
	v_pk_add_f32 v[178:179], v[18:19], v[178:179]
	v_pk_add_f32 v[176:177], v[16:17], v[176:177]
	v_mul_f32_e32 v184, v181, v181
	v_mul_f32_e32 v185, v183, v183
	v_fmac_f32_e32 v184, v180, v180
	v_fmac_f32_e32 v185, v182, v182
	v_add_f32_e32 v184, v184, v185
	v_mul_f32_e32 v185, v177, v177
	v_mul_f32_e32 v186, v179, v179
	v_fmac_f32_e32 v185, v176, v176
	v_fmac_f32_e32 v186, v178, v178
	v_add_f32_e32 v185, v185, v186
	v_add_f32_e32 v184, v184, v185
	v_add_f32_e32 v190, v228, v184
	ds_bpermute_b32 v191, v226, v190
	global_store_dwordx4 v[216:217], v[180:183], off offset:512
	global_store_dwordx4 v[216:217], v[176:179], off offset:528
	v_pk_mul_f32 v[186:187], v[128:129], v[176:177]
	v_pk_mul_f32 v[180:181], v[132:133], v[180:181]
	v_pk_mul_f32 v[182:183], v[134:135], v[182:183]
	s_waitcnt lgkmcnt(0)
	v_add_f32_e32 v176, v190, v191
	ds_bpermute_b32 v177, v227, v176
	v_pk_mul_f32 v[184:185], v[130:131], v[178:179]
	v_cvt_pk_bf16_f32 v178, v180, v181
	v_cvt_pk_bf16_f32 v179, v182, v183
	v_cvt_pk_bf16_f32 v180, v186, v187
	s_nop 0
	v_cvt_pk_bf16_f32 v181, v184, v185
	global_store_dwordx4 v[188:189], v[178:181], off offset:256
	s_and_saveexec_b64 s[34:35], s[8:9]
	s_cbranch_execz .LBB0_998
	s_waitcnt lgkmcnt(0)
	v_add_f32_e32 v178, v176, v177
	v_lshl_add_u64 v[176:177], v[214:215], 2, s[48:49]
	global_atomic_add_f32 v[176:177], v178, off
.LBB0_998:
	s_or_b64 exec, exec, s[34:35]
	s_waitcnt vmcnt(18)
	v_pk_add_f32 v[174:175], v[46:47], v[174:175]
	v_pk_add_f32 v[172:173], v[44:45], v[172:173]
	v_mul_f32_e32 v179, v175, v175
	v_mul_f32_e32 v178, v173, v173
	v_pk_add_f32 v[170:171], v[42:43], v[170:171]
	v_pk_add_f32 v[168:169], v[40:41], v[168:169]
	v_fmac_f32_e32 v178, v172, v172
	v_fmac_f32_e32 v179, v174, v174
	v_add_f32_e32 v178, v178, v179
	v_mul_f32_e32 v179, v169, v169
	v_mul_f32_e32 v180, v171, v171
	s_waitcnt lgkmcnt(0)
	v_lshlrev_b64 v[176:177], 11, v[210:211]
	v_fmac_f32_e32 v179, v168, v168
	v_fmac_f32_e32 v180, v170, v170
	v_lshl_add_u64 v[176:177], v[176:177], 0, v[204:205]
	v_add_f32_e32 v179, v179, v180
	global_store_dwordx4 v[212:213], v[172:175], off
	global_store_dwordx4 v[212:213], v[168:171], off offset:16
	v_add_f32_e32 v180, v178, v179
	v_pk_mul_f32 v[172:173], v[140:141], v[172:173]
	v_pk_mul_f32 v[174:175], v[142:143], v[174:175]
	v_pk_mul_f32 v[178:179], v[138:139], v[170:171]
	v_pk_mul_f32 v[170:171], v[136:137], v[168:169]
	v_cvt_pk_bf16_f32 v168, v172, v173
	v_cvt_pk_bf16_f32 v169, v174, v175
	v_lshl_add_u64 v[172:173], v[176:177], 1, s[46:47]
	s_waitcnt vmcnt(18)
	v_pk_add_f32 v[166:167], v[14:15], v[166:167]
	v_pk_add_f32 v[164:165], v[12:13], v[164:165]
	v_cvt_pk_bf16_f32 v170, v170, v171
	v_cvt_pk_bf16_f32 v171, v178, v179
	global_store_dwordx4 v[172:173], v[168:171], off
	v_pk_add_f32 v[162:163], v[10:11], v[162:163]
	v_pk_add_f32 v[160:161], v[8:9], v[160:161]
	v_mul_f32_e32 v168, v165, v165
	v_mul_f32_e32 v169, v167, v167
	v_fmac_f32_e32 v168, v164, v164
	v_fmac_f32_e32 v169, v166, v166
	v_add_f32_e32 v168, v168, v169
	v_mul_f32_e32 v169, v161, v161
	v_mul_f32_e32 v170, v163, v163
	v_fmac_f32_e32 v169, v160, v160
	v_fmac_f32_e32 v170, v162, v162
	v_add_f32_e32 v169, v169, v170
	v_add_f32_e32 v168, v168, v169
	v_add_f32_e32 v174, v180, v168
	ds_bpermute_b32 v175, v226, v174
	global_store_dwordx4 v[212:213], v[164:167], off offset:512
	global_store_dwordx4 v[212:213], v[160:163], off offset:528
	v_pk_mul_f32 v[170:171], v[128:129], v[160:161]
	v_pk_mul_f32 v[164:165], v[132:133], v[164:165]
	v_pk_mul_f32 v[166:167], v[134:135], v[166:167]
	s_waitcnt lgkmcnt(0)
	v_add_f32_e32 v160, v174, v175
	ds_bpermute_b32 v161, v227, v160
	v_pk_mul_f32 v[168:169], v[130:131], v[162:163]
	v_cvt_pk_bf16_f32 v162, v164, v165
	v_cvt_pk_bf16_f32 v163, v166, v167
	v_cvt_pk_bf16_f32 v164, v170, v171
	s_nop 0
	v_cvt_pk_bf16_f32 v165, v168, v169
	global_store_dwordx4 v[172:173], v[162:165], off offset:256
	s_and_saveexec_b64 s[34:35], s[8:9]
	s_cbranch_execz .LBB0_1000
	s_waitcnt lgkmcnt(0)
	v_add_f32_e32 v162, v160, v161
	v_lshl_add_u64 v[160:161], v[210:211], 2, s[48:49]
	global_atomic_add_f32 v[160:161], v162, off
; __device__ __forceinline__ unsigned pk2(float lo, float hi) { unsigned r; asm volatile("v_cvt_pk_bf16_f32 %0, %1, %2" : "=v"(r) : "v"(lo), "v"(hi)); return r; }
; __device__ __forceinline__ float dot4(f32x4 v) { return (v[0] * v[0] + v[1] * v[1]) + (v[2] * v[2] + v[3] * v[3]); }
;     __device__ __forceinline__ void operator()(const f32x4 (&acc)[2][2][4][2], const Unit& u, int wr, int wc, int fr, int fq) const {
;     ...
;             for (int m = 0; m < 4; ++m) {
;                 const int row = row0 + ai * HALF + m * 16; const size_t off = (size_t)row * D + col0;
;                 float q = 0.f;
; #pragma unroll
;                 for (int bj = 0; bj < 2; ++bj) {
;                     if (quad >= 0 && (quad & 1) != bj) continue;
;                     const f32x4 v0 = rr[m][bj][0] + acc[ai][bj][m][0] * scale, v1 = rr[m][bj][1] + acc[ai][bj][m][1] * scale;
;                     q += dot4(v0) + dot4(v1);
;                     __builtin_nontemporal_store(v0, (f32x4*)(out + off + bj * HALF)); __builtin_nontemporal_store(v1, (f32x4*)(out + off + bj * HALF + 4));
;                     if (An) { const f32x4 a0 = v0 * gv[bj][0], a1 = v1 * gv[bj][1]; u32x4 w; w.x = pk2(a0[0], a0[1]); w.y = pk2(a0[2], a0[3]); w.z = pk2(a1[0], a1[1]); w.w = pk2(a1[2], a1[3]);
;                         *(u32x4*)(An + off + bj * HALF) = w; }
;                 }
;                 q += __shfl_xor(q, 16); q += __shfl_xor(q, 32);
;                 if (fq == 0) __hip_atomic_fetch_add(ss + row, q, __ATOMIC_RELAXED, __HIP_MEMORY_SCOPE_AGENT);
.LBB0_1000:
	s_or_b64 exec, exec, s[34:35]
	s_waitcnt vmcnt(20)
	v_pk_add_f32 v[158:159], v[38:39], v[158:159]
	v_pk_add_f32 v[156:157], v[36:37], v[156:157]
	v_pk_add_f32 v[154:155], v[34:35], v[154:155]
	v_mul_f32_e32 v162, v157, v157
	v_mul_f32_e32 v163, v159, v159
	s_waitcnt lgkmcnt(0)
	v_lshlrev_b64 v[160:161], 11, v[208:209]
	v_pk_add_f32 v[152:153], v[32:33], v[152:153]
	v_fmac_f32_e32 v162, v156, v156
	v_fmac_f32_e32 v163, v158, v158
	v_mul_f32_e32 v164, v155, v155
	v_lshl_add_u64 v[160:161], v[160:161], 0, v[204:205]
	v_add_f32_e32 v162, v162, v163
	v_mul_f32_e32 v163, v153, v153
	v_fmac_f32_e32 v164, v154, v154
	global_store_dwordx4 v[206:207], v[156:159], off
	global_store_dwordx4 v[206:207], v[152:155], off offset:16
	v_fmac_f32_e32 v163, v152, v152
	v_pk_mul_f32 v[142:143], v[142:143], v[158:159]
	v_pk_mul_f32 v[154:155], v[138:139], v[154:155]
	v_pk_mul_f32 v[138:139], v[136:137], v[152:153]
	v_pk_mul_f32 v[140:141], v[140:141], v[156:157]
	v_lshl_add_u64 v[152:153], v[160:161], 1, s[46:47]
	v_cvt_pk_bf16_f32 v136, v140, v141
	v_cvt_pk_bf16_f32 v137, v142, v143
	v_cvt_pk_bf16_f32 v138, v138, v139
	v_cvt_pk_bf16_f32 v139, v154, v155
	global_store_dwordx4 v[152:153], v[136:139], off
	s_waitcnt vmcnt(22)
	v_pk_add_f32 v[140:141], v[0:1], v[144:145]
	v_pk_add_f32 v[142:143], v[2:3], v[146:147]
	s_waitcnt vmcnt(21)
	v_pk_add_f32 v[138:139], v[6:7], v[150:151]
	v_pk_add_f32 v[136:137], v[4:5], v[148:149]
	v_mul_f32_e32 v145, v139, v139
	v_mul_f32_e32 v144, v137, v137
	v_fmac_f32_e32 v144, v136, v136
	v_fmac_f32_e32 v145, v138, v138
	v_add_f32_e32 v144, v144, v145
	v_mul_f32_e32 v145, v141, v141
	v_mul_f32_e32 v146, v143, v143
	v_fmac_f32_e32 v145, v140, v140
	v_fmac_f32_e32 v146, v142, v142
	v_add_f32_e32 v163, v163, v164
	v_add_f32_e32 v145, v145, v146
	v_add_f32_e32 v162, v162, v163
	v_add_f32_e32 v144, v144, v145
	v_add_f32_e32 v144, v162, v144
	ds_bpermute_b32 v145, v226, v144
	global_store_dwordx4 v[206:207], v[136:139], off offset:512
	global_store_dwordx4 v[206:207], v[140:143], off offset:528
	v_pk_mul_f32 v[134:135], v[134:135], v[138:139]
	v_pk_mul_f32 v[138:139], v[128:129], v[140:141]
	v_pk_mul_f32 v[132:133], v[132:133], v[136:137]
	s_waitcnt lgkmcnt(0)
	v_add_f32_e32 v128, v144, v145
	ds_bpermute_b32 v129, v227, v128
	v_pk_mul_f32 v[136:137], v[130:131], v[142:143]
	v_cvt_pk_bf16_f32 v130, v132, v133
	v_cvt_pk_bf16_f32 v131, v134, v135
	v_cvt_pk_bf16_f32 v132, v138, v139
	s_nop 0
	v_cvt_pk_bf16_f32 v133, v136, v137
	global_store_dwordx4 v[152:153], v[130:133], off offset:256
	s_and_saveexec_b64 s[34:35], s[8:9]
	s_cbranch_execz .LBB0_1002
	s_waitcnt lgkmcnt(0)
	v_add_f32_e32 v130, v128, v129
	v_lshl_add_u64 v[128:129], v[208:209], 2, s[48:49]
	global_atomic_add_f32 v[128:129], v130, off

; __device__ __forceinline__ unsigned pk2(float lo, float hi) { unsigned r; asm volatile("v_cvt_pk_bf16_f32 %0, %1, %2" : "=v"(r) : "v"(lo), "v"(hi)); return r; }
; __device__ __forceinline__ float dot4(f32x4 v) { return (v[0] * v[0] + v[1] * v[1]) + (v[2] * v[2] + v[3] * v[3]); }
;     __device__ __forceinline__ void operator()(const f32x4 (&acc)[2][2][4][2], const Unit& u, int wr, int wc, int fr, int fq) const {
;     ...
;                 const int row = row0 + ai * HALF + m * 16; const size_t off = (size_t)row * D + col0;
;                 float q = 0.f;
; #pragma unroll
;                 for (int bj = 0; bj < 2; ++bj) {
;                     if (quad >= 0 && (quad & 1) != bj) continue;
;                     const f32x4 v0 = rr[m][bj][0] + acc[ai][bj][m][0] * scale, v1 = rr[m][bj][1] + acc[ai][bj][m][1] * scale;
;                     q += dot4(v0) + dot4(v1);
;                     __builtin_nontemporal_store(v0, (f32x4*)(out + off + bj * HALF)); __builtin_nontemporal_store(v1, (f32x4*)(out + off + bj * HALF + 4));
;                     if (An) { const f32x4 a0 = v0 * gv[bj][0], a1 = v1 * gv[bj][1]; u32x4 w; w.x = pk2(a0[0], a0[1]); w.y = pk2(a0[2], a0[3]); w.z = pk2(a1[0], a1[1]); w.w = pk2(a1[2], a1[3]);
;                         *(u32x4*)(An + off + bj * HALF) = w; }
;                 }
; __device__ __forceinline__ void ph_res_fix(int ph) {
;     ...
;                 for (int n = 0; n < 2; ++n) if (a * 2 + b == quad) acc[a][b][m][n] = s[m * 2 + n];
.LBB0_1077:
	s_cmp_eq_u32 s3, 0
	s_cselect_b64 s[14:15], -1, 0
	v_lshlrev_b64 v[124:125], 11, v[116:117]
	v_lshl_add_u64 v[130:131], v[124:125], 0, v[92:93]
	v_mov_b32_e32 v128, 0
	s_and_b64 vcc, exec, s[12:13]
	v_lshl_add_u64 v[126:127], v[124:125], 2, v[98:99]
	v_lshl_add_u64 v[124:125], v[130:131], 1, s[20:21]
	s_cbranch_vccnz .LBB0_1079
	v_cndmask_b32_e64 v129, 0, v111, s[14:15]
	v_cndmask_b32_e64 v128, 0, v110, s[14:15]
	v_cndmask_b32_e64 v133, 0, v115, s[14:15]
	v_cndmask_b32_e64 v132, 0, v114, s[14:15]
	v_cndmask_b32_e64 v131, 0, v109, s[14:15]
	v_cndmask_b32_e64 v130, 0, v108, s[14:15]
	v_cndmask_b32_e64 v135, 0, v113, s[14:15]
	v_cndmask_b32_e64 v134, 0, v112, s[14:15]
	s_waitcnt vmcnt(0)
	v_pk_add_f32 v[76:77], v[76:77], v[128:129]
	v_pk_add_f32 v[72:73], v[72:73], v[132:133]
	v_pk_add_f32 v[78:79], v[78:79], v[130:131]
	v_pk_add_f32 v[74:75], v[74:75], v[134:135]
	v_mov_b32_e32 v130, v77
	v_mov_b32_e32 v131, v73
	v_mov_b32_e32 v128, v76
	v_mov_b32_e32 v129, v72
	v_pk_mul_f32 v[130:131], v[130:131], v[130:131]
	v_mov_b32_e32 v132, v79
	v_mov_b32_e32 v133, v75
	v_pk_fma_f32 v[128:129], v[128:129], v[128:129], v[130:131]
	v_mov_b32_e32 v130, v78
	v_mov_b32_e32 v131, v74
	v_pk_mul_f32 v[132:133], v[132:133], v[132:133]
	global_store_dwordx4 v[126:127], v[76:79], off
	global_store_dwordx4 v[126:127], v[72:75], off offset:16
	v_pk_fma_f32 v[130:131], v[130:131], v[130:131], v[132:133]
	v_pk_mul_f32 v[78:79], v[14:15], v[78:79]
	v_pk_add_f32 v[128:129], v[128:129], v[130:131]
	v_pk_mul_f32 v[130:131], v[10:11], v[74:75]
	v_add_f32_e32 v128, v128, v129
	v_pk_mul_f32 v[74:75], v[8:9], v[72:73]
	v_pk_mul_f32 v[76:77], v[12:13], v[76:77]
	s_nop 0
	v_cvt_pk_bf16_f32 v72, v76, v77
	v_cvt_pk_bf16_f32 v73, v78, v79
	v_cvt_pk_bf16_f32 v74, v74, v75
	v_cvt_pk_bf16_f32 v75, v130, v131
	global_store_dwordx4 v[124:125], v[72:75], off
.LBB0_1079:
	s_cmp_eq_u32 s3, 1
	s_cselect_b64 s[16:17], -1, 0
	s_and_b64 vcc, exec, s[10:11]
	s_cbranch_vccnz .LBB0_1081
	s_waitcnt vmcnt(1)
	v_cndmask_b32_e64 v73, 0, v111, s[16:17]
	v_cndmask_b32_e64 v72, 0, v110, s[16:17]
	s_waitcnt vmcnt(0)
	v_cndmask_b32_e64 v77, 0, v115, s[16:17]
	v_cndmask_b32_e64 v76, 0, v114, s[16:17]
	v_cndmask_b32_e64 v75, 0, v109, s[16:17]
	v_cndmask_b32_e64 v74, 0, v108, s[16:17]
	v_cndmask_b32_e64 v79, 0, v113, s[16:17]
	v_cndmask_b32_e64 v78, 0, v112, s[16:17]
	v_pk_add_f32 v[68:69], v[68:69], v[72:73]
	v_pk_add_f32 v[64:65], v[64:65], v[76:77]
	v_pk_add_f32 v[70:71], v[70:71], v[74:75]
	v_pk_add_f32 v[66:67], v[66:67], v[78:79]
	v_mov_b32_e32 v74, v69
	v_mov_b32_e32 v75, v65
	v_mov_b32_e32 v72, v68
	v_mov_b32_e32 v73, v64
	v_pk_mul_f32 v[74:75], v[74:75], v[74:75]
	v_mov_b32_e32 v76, v71
	v_mov_b32_e32 v77, v67
	v_pk_fma_f32 v[72:73], v[72:73], v[72:73], v[74:75]
	v_mov_b32_e32 v74, v70
	v_mov_b32_e32 v75, v66
	v_pk_mul_f32 v[76:77], v[76:77], v[76:77]
	global_store_dwordx4 v[126:127], v[68:71], off offset:512
	global_store_dwordx4 v[126:127], v[64:67], off offset:528
	v_pk_fma_f32 v[74:75], v[74:75], v[74:75], v[76:77]
	v_pk_mul_f32 v[70:71], v[6:7], v[70:71]
	v_pk_add_f32 v[72:73], v[72:73], v[74:75]
	v_pk_mul_f32 v[68:69], v[4:5], v[68:69]
	v_add_f32_e32 v72, v72, v73
	v_add_f32_e32 v128, v128, v72
	v_pk_mul_f32 v[72:73], v[2:3], v[66:67]
	v_pk_mul_f32 v[66:67], v[0:1], v[64:65]
	v_cvt_pk_bf16_f32 v64, v68, v69
	v_cvt_pk_bf16_f32 v65, v70, v71
	s_nop 0
	v_cvt_pk_bf16_f32 v66, v66, v67
	v_cvt_pk_bf16_f32 v67, v72, v73
	global_store_dwordx4 v[124:125], v[64:67], off offset:256

; __device__ __forceinline__ unsigned pk2(float lo, float hi) { unsigned r; asm volatile("v_cvt_pk_bf16_f32 %0, %1, %2" : "=v"(r) : "v"(lo), "v"(hi)); return r; }
; __device__ __forceinline__ float dot4(f32x4 v) { return (v[0] * v[0] + v[1] * v[1]) + (v[2] * v[2] + v[3] * v[3]); }
;     __device__ __forceinline__ void operator()(const f32x4 (&acc)[2][2][4][2], const Unit& u, int wr, int wc, int fr, int fq) const {
;     ...
;                 const int row = row0 + ai * HALF + m * 16; const size_t off = (size_t)row * D + col0;
;                 float q = 0.f;
; #pragma unroll
;                 for (int bj = 0; bj < 2; ++bj) {
;                     if (quad >= 0 && (quad & 1) != bj) continue;
;                     const f32x4 v0 = rr[m][bj][0] + acc[ai][bj][m][0] * scale, v1 = rr[m][bj][1] + acc[ai][bj][m][1] * scale;
;                     q += dot4(v0) + dot4(v1);
;                     __builtin_nontemporal_store(v0, (f32x4*)(out + off + bj * HALF)); __builtin_nontemporal_store(v1, (f32x4*)(out + off + bj * HALF + 4));
;                     if (An) { const f32x4 a0 = v0 * gv[bj][0], a1 = v1 * gv[bj][1]; u32x4 w; w.x = pk2(a0[0], a0[1]); w.y = pk2(a0[2], a0[3]); w.z = pk2(a1[0], a1[1]); w.w = pk2(a1[2], a1[3]);
;                         *(u32x4*)(An + off + bj * HALF) = w; }
;                 }
; __device__ __forceinline__ void ph_res_fix(int ph) {
;     ...
;                 for (int n = 0; n < 2; ++n) if (a * 2 + b == quad) acc[a][b][m][n] = s[m * 2 + n];
.LBB0_1083:
	s_or_b64 exec, exec, s[34:35]
	s_waitcnt lgkmcnt(0)
	v_lshlrev_b64 v[64:65], 11, v[122:123]
	v_lshl_add_u64 v[72:73], v[64:65], 0, v[92:93]
	v_mov_b32_e32 v70, 0
	s_and_b64 vcc, exec, s[12:13]
	v_lshl_add_u64 v[66:67], v[64:65], 2, v[98:99]
	v_lshl_add_u64 v[64:65], v[72:73], 1, s[20:21]
	s_cbranch_vccnz .LBB0_1085
	v_cndmask_b32_e64 v71, 0, v97, s[14:15]
	v_cndmask_b32_e64 v70, 0, v96, s[14:15]
	v_cndmask_b32_e64 v75, 0, v103, s[14:15]
	v_cndmask_b32_e64 v74, 0, v102, s[14:15]
	v_cndmask_b32_e64 v73, 0, v95, s[14:15]
	v_cndmask_b32_e64 v72, 0, v94, s[14:15]
	v_cndmask_b32_e64 v77, 0, v101, s[14:15]
	v_cndmask_b32_e64 v76, 0, v100, s[14:15]
	v_pk_add_f32 v[60:61], v[60:61], v[70:71]
	v_pk_add_f32 v[56:57], v[56:57], v[74:75]
	v_pk_add_f32 v[62:63], v[62:63], v[72:73]
	v_pk_add_f32 v[58:59], v[58:59], v[76:77]
	v_mov_b32_e32 v72, v61
	v_mov_b32_e32 v73, v57
	v_mov_b32_e32 v70, v60
	v_mov_b32_e32 v71, v56
	v_pk_mul_f32 v[72:73], v[72:73], v[72:73]
	v_mov_b32_e32 v74, v63
	v_mov_b32_e32 v75, v59
	v_pk_fma_f32 v[70:71], v[70:71], v[70:71], v[72:73]
	v_mov_b32_e32 v72, v62
	v_mov_b32_e32 v73, v58
	v_pk_mul_f32 v[74:75], v[74:75], v[74:75]
	global_store_dwordx4 v[66:67], v[60:63], off
	global_store_dwordx4 v[66:67], v[56:59], off offset:16
	v_pk_fma_f32 v[72:73], v[72:73], v[72:73], v[74:75]
	v_pk_mul_f32 v[62:63], v[14:15], v[62:63]
	v_pk_add_f32 v[70:71], v[70:71], v[72:73]
	v_pk_mul_f32 v[72:73], v[10:11], v[58:59]
	v_add_f32_e32 v70, v70, v71
	v_pk_mul_f32 v[58:59], v[8:9], v[56:57]
	v_pk_mul_f32 v[60:61], v[12:13], v[60:61]
	s_nop 0
	v_cvt_pk_bf16_f32 v56, v60, v61
	v_cvt_pk_bf16_f32 v57, v62, v63
	v_cvt_pk_bf16_f32 v58, v58, v59
	v_cvt_pk_bf16_f32 v59, v72, v73
	global_store_dwordx4 v[64:65], v[56:59], off
.LBB0_1085:
	s_and_b64 vcc, exec, s[10:11]
	s_cbranch_vccnz .LBB0_1087
	v_cndmask_b32_e64 v57, 0, v97, s[16:17]
	v_cndmask_b32_e64 v56, 0, v96, s[16:17]
	v_cndmask_b32_e64 v61, 0, v103, s[16:17]
	v_cndmask_b32_e64 v60, 0, v102, s[16:17]
	v_cndmask_b32_e64 v59, 0, v95, s[16:17]
	v_cndmask_b32_e64 v58, 0, v94, s[16:17]
	v_cndmask_b32_e64 v63, 0, v101, s[16:17]
	v_cndmask_b32_e64 v62, 0, v100, s[16:17]
	v_pk_add_f32 v[52:53], v[52:53], v[56:57]
	v_pk_add_f32 v[48:49], v[48:49], v[60:61]
	v_pk_add_f32 v[54:55], v[54:55], v[58:59]
	v_pk_add_f32 v[50:51], v[50:51], v[62:63]
	v_mov_b32_e32 v58, v53
	v_mov_b32_e32 v59, v49
	v_mov_b32_e32 v56, v52
	v_mov_b32_e32 v57, v48
	v_pk_mul_f32 v[58:59], v[58:59], v[58:59]
	v_mov_b32_e32 v60, v55
	v_mov_b32_e32 v61, v51
	v_pk_fma_f32 v[56:57], v[56:57], v[56:57], v[58:59]
	v_mov_b32_e32 v58, v54
	v_mov_b32_e32 v59, v50
	v_pk_mul_f32 v[60:61], v[60:61], v[60:61]
	global_store_dwordx4 v[66:67], v[52:55], off offset:512
	global_store_dwordx4 v[66:67], v[48:51], off offset:528
	v_pk_fma_f32 v[58:59], v[58:59], v[58:59], v[60:61]
	v_pk_mul_f32 v[54:55], v[6:7], v[54:55]
	v_pk_add_f32 v[56:57], v[56:57], v[58:59]
	v_pk_mul_f32 v[52:53], v[4:5], v[52:53]
	v_add_f32_e32 v56, v56, v57
	v_add_f32_e32 v70, v70, v56
	v_pk_mul_f32 v[56:57], v[2:3], v[50:51]
	v_pk_mul_f32 v[50:51], v[0:1], v[48:49]
	v_cvt_pk_bf16_f32 v48, v52, v53
	v_cvt_pk_bf16_f32 v49, v54, v55
	s_nop 0
	v_cvt_pk_bf16_f32 v50, v50, v51
	v_cvt_pk_bf16_f32 v51, v56, v57
	global_store_dwordx4 v[64:65], v[48:51], off offset:256

; __device__ __forceinline__ unsigned pk2(float lo, float hi) { unsigned r; asm volatile("v_cvt_pk_bf16_f32 %0, %1, %2" : "=v"(r) : "v"(lo), "v"(hi)); return r; }
; __device__ __forceinline__ float dot4(f32x4 v) { return (v[0] * v[0] + v[1] * v[1]) + (v[2] * v[2] + v[3] * v[3]); }
;     __device__ __forceinline__ void operator()(const f32x4 (&acc)[2][2][4][2], const Unit& u, int wr, int wc, int fr, int fq) const {
;     ...
;                 const int row = row0 + ai * HALF + m * 16; const size_t off = (size_t)row * D + col0;
;                 float q = 0.f;
; #pragma unroll
;                 for (int bj = 0; bj < 2; ++bj) {
;                     if (quad >= 0 && (quad & 1) != bj) continue;
;                     const f32x4 v0 = rr[m][bj][0] + acc[ai][bj][m][0] * scale, v1 = rr[m][bj][1] + acc[ai][bj][m][1] * scale;
;                     q += dot4(v0) + dot4(v1);
;                     __builtin_nontemporal_store(v0, (f32x4*)(out + off + bj * HALF)); __builtin_nontemporal_store(v1, (f32x4*)(out + off + bj * HALF + 4));
;                     if (An) { const f32x4 a0 = v0 * gv[bj][0], a1 = v1 * gv[bj][1]; u32x4 w; w.x = pk2(a0[0], a0[1]); w.y = pk2(a0[2], a0[3]); w.z = pk2(a1[0], a1[1]); w.w = pk2(a1[2], a1[3]);
;                         *(u32x4*)(An + off + bj * HALF) = w; }
;                 }
; __device__ __forceinline__ void ph_res_fix(int ph) {
;     ...
;                 for (int n = 0; n < 2; ++n) if (a * 2 + b == quad) acc[a][b][m][n] = s[m * 2 + n];
.LBB0_1089:
	s_or_b64 exec, exec, s[34:35]
	s_waitcnt lgkmcnt(0)
	v_lshlrev_b64 v[48:49], 11, v[120:121]
	v_lshl_add_u64 v[54:55], v[48:49], 0, v[92:93]
	v_mov_b32_e32 v52, 0
	s_and_b64 vcc, exec, s[12:13]
	v_lshl_add_u64 v[50:51], v[48:49], 2, v[98:99]
	v_lshl_add_u64 v[48:49], v[54:55], 1, s[20:21]
	s_cbranch_vccnz .LBB0_1091
	v_cndmask_b32_e64 v53, 0, v87, s[14:15]
	v_cndmask_b32_e64 v52, 0, v86, s[14:15]
	v_cndmask_b32_e64 v57, 0, v107, s[14:15]
	v_cndmask_b32_e64 v56, 0, v106, s[14:15]
	v_cndmask_b32_e64 v55, 0, v85, s[14:15]
	v_cndmask_b32_e64 v54, 0, v84, s[14:15]
	v_cndmask_b32_e64 v59, 0, v105, s[14:15]
	v_cndmask_b32_e64 v58, 0, v104, s[14:15]
	v_pk_add_f32 v[44:45], v[44:45], v[52:53]
	v_pk_add_f32 v[40:41], v[40:41], v[56:57]
	v_pk_add_f32 v[46:47], v[46:47], v[54:55]
	v_pk_add_f32 v[42:43], v[42:43], v[58:59]
	v_mov_b32_e32 v54, v45
	v_mov_b32_e32 v55, v41
	v_mov_b32_e32 v52, v44
	v_mov_b32_e32 v53, v40
	v_pk_mul_f32 v[54:55], v[54:55], v[54:55]
	v_mov_b32_e32 v56, v47
	v_mov_b32_e32 v57, v43
	v_pk_fma_f32 v[52:53], v[52:53], v[52:53], v[54:55]
	v_mov_b32_e32 v54, v46
	v_mov_b32_e32 v55, v42
	v_pk_mul_f32 v[56:57], v[56:57], v[56:57]
	global_store_dwordx4 v[50:51], v[44:47], off
	global_store_dwordx4 v[50:51], v[40:43], off offset:16
	v_pk_fma_f32 v[54:55], v[54:55], v[54:55], v[56:57]
	v_pk_mul_f32 v[46:47], v[14:15], v[46:47]
	v_pk_add_f32 v[52:53], v[52:53], v[54:55]
	v_pk_mul_f32 v[54:55], v[10:11], v[42:43]
	v_add_f32_e32 v52, v52, v53
	v_pk_mul_f32 v[42:43], v[8:9], v[40:41]
	v_pk_mul_f32 v[44:45], v[12:13], v[44:45]
	s_nop 0
	v_cvt_pk_bf16_f32 v40, v44, v45
	v_cvt_pk_bf16_f32 v41, v46, v47
	v_cvt_pk_bf16_f32 v42, v42, v43
	v_cvt_pk_bf16_f32 v43, v54, v55
	global_store_dwordx4 v[48:49], v[40:43], off
.LBB0_1091:
	s_and_b64 vcc, exec, s[10:11]
	s_cbranch_vccnz .LBB0_1093
	v_cndmask_b32_e64 v41, 0, v87, s[16:17]
	v_cndmask_b32_e64 v40, 0, v86, s[16:17]
	v_cndmask_b32_e64 v45, 0, v107, s[16:17]
	v_cndmask_b32_e64 v44, 0, v106, s[16:17]
	v_cndmask_b32_e64 v43, 0, v85, s[16:17]
	v_cndmask_b32_e64 v42, 0, v84, s[16:17]
	v_cndmask_b32_e64 v47, 0, v105, s[16:17]
	v_cndmask_b32_e64 v46, 0, v104, s[16:17]
	v_pk_add_f32 v[36:37], v[36:37], v[40:41]
	v_pk_add_f32 v[32:33], v[32:33], v[44:45]
	v_pk_add_f32 v[38:39], v[38:39], v[42:43]
	v_pk_add_f32 v[34:35], v[34:35], v[46:47]
	v_mov_b32_e32 v42, v37
	v_mov_b32_e32 v43, v33
	v_mov_b32_e32 v40, v36
	v_mov_b32_e32 v41, v32
	v_pk_mul_f32 v[42:43], v[42:43], v[42:43]
	v_mov_b32_e32 v44, v39
	v_mov_b32_e32 v45, v35
	v_pk_fma_f32 v[40:41], v[40:41], v[40:41], v[42:43]
	v_mov_b32_e32 v42, v38
	v_mov_b32_e32 v43, v34
	v_pk_mul_f32 v[44:45], v[44:45], v[44:45]
	global_store_dwordx4 v[50:51], v[36:39], off offset:512
	global_store_dwordx4 v[50:51], v[32:35], off offset:528
	v_pk_fma_f32 v[42:43], v[42:43], v[42:43], v[44:45]
	v_pk_mul_f32 v[38:39], v[6:7], v[38:39]
	v_pk_add_f32 v[40:41], v[40:41], v[42:43]
	v_pk_mul_f32 v[36:37], v[4:5], v[36:37]
	v_add_f32_e32 v40, v40, v41
	v_add_f32_e32 v52, v52, v40
	v_pk_mul_f32 v[40:41], v[2:3], v[34:35]
	v_pk_mul_f32 v[34:35], v[0:1], v[32:33]
	v_cvt_pk_bf16_f32 v32, v36, v37
	v_cvt_pk_bf16_f32 v33, v38, v39
	s_nop 0
	v_cvt_pk_bf16_f32 v34, v34, v35
	v_cvt_pk_bf16_f32 v35, v40, v41
	global_store_dwordx4 v[48:49], v[32:35], off offset:256

; __device__ __forceinline__ unsigned pk2(float lo, float hi) { unsigned r; asm volatile("v_cvt_pk_bf16_f32 %0, %1, %2" : "=v"(r) : "v"(lo), "v"(hi)); return r; }
; __device__ __forceinline__ float dot4(f32x4 v) { return (v[0] * v[0] + v[1] * v[1]) + (v[2] * v[2] + v[3] * v[3]); }
;     __device__ __forceinline__ void operator()(const f32x4 (&acc)[2][2][4][2], const Unit& u, int wr, int wc, int fr, int fq) const {
;     ...
;                 const int row = row0 + ai * HALF + m * 16; const size_t off = (size_t)row * D + col0;
;                 float q = 0.f;
; #pragma unroll
;                 for (int bj = 0; bj < 2; ++bj) {
;                     if (quad >= 0 && (quad & 1) != bj) continue;
;                     const f32x4 v0 = rr[m][bj][0] + acc[ai][bj][m][0] * scale, v1 = rr[m][bj][1] + acc[ai][bj][m][1] * scale;
;                     q += dot4(v0) + dot4(v1);
;                     __builtin_nontemporal_store(v0, (f32x4*)(out + off + bj * HALF)); __builtin_nontemporal_store(v1, (f32x4*)(out + off + bj * HALF + 4));
;                     if (An) { const f32x4 a0 = v0 * gv[bj][0], a1 = v1 * gv[bj][1]; u32x4 w; w.x = pk2(a0[0], a0[1]); w.y = pk2(a0[2], a0[3]); w.z = pk2(a1[0], a1[1]); w.w = pk2(a1[2], a1[3]);
;                         *(u32x4*)(An + off + bj * HALF) = w; }
;                 }
; __device__ __forceinline__ void ph_res_fix(int ph) {
;     ...
;                 for (int n = 0; n < 2; ++n) if (a * 2 + b == quad) acc[a][b][m][n] = s[m * 2 + n];
.LBB0_1095:
	s_or_b64 exec, exec, s[34:35]
	s_waitcnt lgkmcnt(0)
	v_lshlrev_b64 v[32:33], 11, v[118:119]
	v_lshl_add_u64 v[38:39], v[32:33], 0, v[92:93]
	v_mov_b32_e32 v36, 0
	s_and_b64 vcc, exec, s[12:13]
	v_lshl_add_u64 v[34:35], v[32:33], 2, v[98:99]
	v_lshl_add_u64 v[32:33], v[38:39], 1, s[20:21]
	s_cbranch_vccnz .LBB0_1097
	v_cndmask_b32_e64 v37, 0, v83, s[14:15]
	v_cndmask_b32_e64 v36, 0, v82, s[14:15]
	v_cndmask_b32_e64 v41, 0, v91, s[14:15]
	v_cndmask_b32_e64 v40, 0, v90, s[14:15]
	v_cndmask_b32_e64 v39, 0, v81, s[14:15]
	v_cndmask_b32_e64 v38, 0, v80, s[14:15]
	v_cndmask_b32_e64 v43, 0, v89, s[14:15]
	v_cndmask_b32_e64 v42, 0, v88, s[14:15]
	v_pk_add_f32 v[28:29], v[28:29], v[36:37]
	v_pk_add_f32 v[24:25], v[24:25], v[40:41]
	v_pk_add_f32 v[30:31], v[30:31], v[38:39]
	v_pk_add_f32 v[26:27], v[26:27], v[42:43]
	v_mov_b32_e32 v38, v29
	v_mov_b32_e32 v39, v25
	v_mov_b32_e32 v36, v28
	v_mov_b32_e32 v37, v24
	v_pk_mul_f32 v[38:39], v[38:39], v[38:39]
	v_mov_b32_e32 v40, v31
	v_mov_b32_e32 v41, v27
	v_pk_fma_f32 v[36:37], v[36:37], v[36:37], v[38:39]
	v_mov_b32_e32 v38, v30
	v_mov_b32_e32 v39, v26
	v_pk_mul_f32 v[40:41], v[40:41], v[40:41]
	global_store_dwordx4 v[34:35], v[28:31], off
	global_store_dwordx4 v[34:35], v[24:27], off offset:16
	v_pk_fma_f32 v[38:39], v[38:39], v[38:39], v[40:41]
	v_pk_mul_f32 v[30:31], v[14:15], v[30:31]
	v_pk_add_f32 v[36:37], v[36:37], v[38:39]
	v_pk_mul_f32 v[38:39], v[10:11], v[26:27]
	v_add_f32_e32 v36, v36, v37
	v_pk_mul_f32 v[26:27], v[8:9], v[24:25]
	v_pk_mul_f32 v[28:29], v[12:13], v[28:29]
	s_nop 0
	v_cvt_pk_bf16_f32 v24, v28, v29
	v_cvt_pk_bf16_f32 v25, v30, v31
	v_cvt_pk_bf16_f32 v26, v26, v27
	v_cvt_pk_bf16_f32 v27, v38, v39
	global_store_dwordx4 v[32:33], v[24:27], off
.LBB0_1097:
	s_and_b64 vcc, exec, s[10:11]
	s_cbranch_vccnz .LBB0_1099
	v_cndmask_b32_e64 v25, 0, v83, s[16:17]
	v_cndmask_b32_e64 v24, 0, v82, s[16:17]
	v_cndmask_b32_e64 v29, 0, v91, s[16:17]
	v_cndmask_b32_e64 v28, 0, v90, s[16:17]
	v_cndmask_b32_e64 v27, 0, v81, s[16:17]
	v_cndmask_b32_e64 v26, 0, v80, s[16:17]
	v_cndmask_b32_e64 v31, 0, v89, s[16:17]
	v_cndmask_b32_e64 v30, 0, v88, s[16:17]
	v_pk_add_f32 v[20:21], v[20:21], v[24:25]
	v_pk_add_f32 v[16:17], v[16:17], v[28:29]
	v_pk_add_f32 v[22:23], v[22:23], v[26:27]
	v_pk_add_f32 v[18:19], v[18:19], v[30:31]
	v_mov_b32_e32 v26, v21
	v_mov_b32_e32 v27, v17
	v_mov_b32_e32 v24, v20
	v_mov_b32_e32 v25, v16
	v_pk_mul_f32 v[26:27], v[26:27], v[26:27]
	v_mov_b32_e32 v28, v23
	v_mov_b32_e32 v29, v19
	v_pk_fma_f32 v[24:25], v[24:25], v[24:25], v[26:27]
	v_mov_b32_e32 v26, v22
	v_mov_b32_e32 v27, v18
	v_pk_mul_f32 v[28:29], v[28:29], v[28:29]
	global_store_dwordx4 v[34:35], v[20:23], off offset:512
	global_store_dwordx4 v[34:35], v[16:19], off offset:528
	v_pk_fma_f32 v[26:27], v[26:27], v[26:27], v[28:29]
	v_pk_mul_f32 v[22:23], v[6:7], v[22:23]
	v_pk_add_f32 v[24:25], v[24:25], v[26:27]
	v_pk_mul_f32 v[20:21], v[4:5], v[20:21]
	v_add_f32_e32 v24, v24, v25
	v_add_f32_e32 v36, v36, v24
	v_pk_mul_f32 v[24:25], v[2:3], v[18:19]
	v_pk_mul_f32 v[18:19], v[0:1], v[16:17]
	v_cvt_pk_bf16_f32 v16, v20, v21
	v_cvt_pk_bf16_f32 v17, v22, v23
	s_nop 0
	v_cvt_pk_bf16_f32 v18, v18, v19
	v_cvt_pk_bf16_f32 v19, v24, v25
	global_store_dwordx4 v[32:33], v[16:19], off offset:256

; __device__ __forceinline__ unsigned pk2(float lo, float hi) { unsigned r; asm volatile("v_cvt_pk_bf16_f32 %0, %1, %2" : "=v"(r) : "v"(lo), "v"(hi)); return r; }
; __device__ __forceinline__ float dot4(f32x4 v) { return (v[0] * v[0] + v[1] * v[1]) + (v[2] * v[2] + v[3] * v[3]); }
;     __device__ __forceinline__ void operator()(const f32x4 (&acc)[2][2][4][2], const Unit& u, int wr, int wc, int fr, int fq) const {
;     ...
;                 const int row = row0 + ai * HALF + m * 16; const size_t off = (size_t)row * D + col0;
;                 float q = 0.f;
; #pragma unroll
;                 for (int bj = 0; bj < 2; ++bj) {
;                     if (quad >= 0 && (quad & 1) != bj) continue;
;                     const f32x4 v0 = rr[m][bj][0] + acc[ai][bj][m][0] * scale, v1 = rr[m][bj][1] + acc[ai][bj][m][1] * scale;
;                     q += dot4(v0) + dot4(v1);
;                     __builtin_nontemporal_store(v0, (f32x4*)(out + off + bj * HALF)); __builtin_nontemporal_store(v1, (f32x4*)(out + off + bj * HALF + 4));
;                     if (An) { const f32x4 a0 = v0 * gv[bj][0], a1 = v1 * gv[bj][1]; u32x4 w; w.x = pk2(a0[0], a0[1]); w.y = pk2(a0[2], a0[3]); w.z = pk2(a1[0], a1[1]); w.w = pk2(a1[2], a1[3]);
;                         *(u32x4*)(An + off + bj * HALF) = w; }
;                 }
; __device__ __forceinline__ void ph_res_fix(int ph) {
;     ...
;                 for (int n = 0; n < 2; ++n) if (a * 2 + b == quad) acc[a][b][m][n] = s[m * 2 + n];
.LBB0_1119:
	s_cmp_eq_u32 s3, 2
	s_cselect_b64 s[14:15], -1, 0
	v_lshlrev_b64 v[124:125], 11, v[122:123]
	v_lshl_add_u64 v[130:131], v[124:125], 0, v[92:93]
	v_mov_b32_e32 v128, 0
	s_and_b64 vcc, exec, s[12:13]
	v_lshl_add_u64 v[126:127], v[124:125], 2, v[98:99]
	v_lshl_add_u64 v[124:125], v[130:131], 1, s[20:21]
	s_cbranch_vccnz .LBB0_1121
	v_cndmask_b32_e64 v129, 0, v111, s[14:15]
	v_cndmask_b32_e64 v128, 0, v110, s[14:15]
	v_cndmask_b32_e64 v133, 0, v115, s[14:15]
	v_cndmask_b32_e64 v132, 0, v114, s[14:15]
	v_cndmask_b32_e64 v131, 0, v109, s[14:15]
	v_cndmask_b32_e64 v130, 0, v108, s[14:15]
	v_cndmask_b32_e64 v135, 0, v113, s[14:15]
	v_cndmask_b32_e64 v134, 0, v112, s[14:15]
	s_waitcnt vmcnt(0)
	v_pk_add_f32 v[76:77], v[76:77], v[128:129]
	v_pk_add_f32 v[72:73], v[72:73], v[132:133]
	v_pk_add_f32 v[78:79], v[78:79], v[130:131]
	v_pk_add_f32 v[74:75], v[74:75], v[134:135]
	v_mov_b32_e32 v130, v77
	v_mov_b32_e32 v131, v73
	v_mov_b32_e32 v128, v76
	v_mov_b32_e32 v129, v72
	v_pk_mul_f32 v[130:131], v[130:131], v[130:131]
	v_mov_b32_e32 v132, v79
	v_mov_b32_e32 v133, v75
	v_pk_fma_f32 v[128:129], v[128:129], v[128:129], v[130:131]
	v_mov_b32_e32 v130, v78
	v_mov_b32_e32 v131, v74
	v_pk_mul_f32 v[132:133], v[132:133], v[132:133]
	global_store_dwordx4 v[126:127], v[76:79], off
	global_store_dwordx4 v[126:127], v[72:75], off offset:16
	v_pk_fma_f32 v[130:131], v[130:131], v[130:131], v[132:133]
	v_pk_mul_f32 v[78:79], v[14:15], v[78:79]
	v_pk_add_f32 v[128:129], v[128:129], v[130:131]
	v_pk_mul_f32 v[130:131], v[10:11], v[74:75]
	v_add_f32_e32 v128, v128, v129
	v_pk_mul_f32 v[74:75], v[8:9], v[72:73]
	v_pk_mul_f32 v[76:77], v[12:13], v[76:77]
	s_nop 0
	v_cvt_pk_bf16_f32 v72, v76, v77
	v_cvt_pk_bf16_f32 v73, v78, v79
	v_cvt_pk_bf16_f32 v74, v74, v75
	v_cvt_pk_bf16_f32 v75, v130, v131
	global_store_dwordx4 v[124:125], v[72:75], off
.LBB0_1121:
	s_cmp_eq_u32 s3, 3
	s_cselect_b64 s[16:17], -1, 0
	s_and_b64 vcc, exec, s[10:11]
	s_cbranch_vccnz .LBB0_1123
	s_waitcnt vmcnt(1)
	v_cndmask_b32_e64 v73, 0, v111, s[16:17]
	v_cndmask_b32_e64 v72, 0, v110, s[16:17]
	s_waitcnt vmcnt(0)
	v_cndmask_b32_e64 v77, 0, v115, s[16:17]
	v_cndmask_b32_e64 v76, 0, v114, s[16:17]
	v_cndmask_b32_e64 v75, 0, v109, s[16:17]
	v_cndmask_b32_e64 v74, 0, v108, s[16:17]
	v_cndmask_b32_e64 v79, 0, v113, s[16:17]
	v_cndmask_b32_e64 v78, 0, v112, s[16:17]
	v_pk_add_f32 v[68:69], v[68:69], v[72:73]
	v_pk_add_f32 v[64:65], v[64:65], v[76:77]
	v_pk_add_f32 v[70:71], v[70:71], v[74:75]
	v_pk_add_f32 v[66:67], v[66:67], v[78:79]
	v_mov_b32_e32 v74, v69
	v_mov_b32_e32 v75, v65
	v_mov_b32_e32 v72, v68
	v_mov_b32_e32 v73, v64
	v_pk_mul_f32 v[74:75], v[74:75], v[74:75]
	v_mov_b32_e32 v76, v71
	v_mov_b32_e32 v77, v67
	v_pk_fma_f32 v[72:73], v[72:73], v[72:73], v[74:75]
	v_mov_b32_e32 v74, v70
	v_mov_b32_e32 v75, v66
	v_pk_mul_f32 v[76:77], v[76:77], v[76:77]
	global_store_dwordx4 v[126:127], v[68:71], off offset:512
	global_store_dwordx4 v[126:127], v[64:67], off offset:528
	v_pk_fma_f32 v[74:75], v[74:75], v[74:75], v[76:77]
	v_pk_mul_f32 v[70:71], v[6:7], v[70:71]
	v_pk_add_f32 v[72:73], v[72:73], v[74:75]
	v_pk_mul_f32 v[68:69], v[4:5], v[68:69]
	v_add_f32_e32 v72, v72, v73
	v_add_f32_e32 v128, v128, v72
	v_pk_mul_f32 v[72:73], v[2:3], v[66:67]
	v_pk_mul_f32 v[66:67], v[0:1], v[64:65]
	v_cvt_pk_bf16_f32 v64, v68, v69
	v_cvt_pk_bf16_f32 v65, v70, v71
	s_nop 0
	v_cvt_pk_bf16_f32 v66, v66, v67
	v_cvt_pk_bf16_f32 v67, v72, v73
	global_store_dwordx4 v[124:125], v[64:67], off offset:256

; __device__ __forceinline__ unsigned pk2(float lo, float hi) { unsigned r; asm volatile("v_cvt_pk_bf16_f32 %0, %1, %2" : "=v"(r) : "v"(lo), "v"(hi)); return r; }
; __device__ __forceinline__ float dot4(f32x4 v) { return (v[0] * v[0] + v[1] * v[1]) + (v[2] * v[2] + v[3] * v[3]); }
;     __device__ __forceinline__ void operator()(const f32x4 (&acc)[2][2][4][2], const Unit& u, int wr, int wc, int fr, int fq) const {
;     ...
;                 const int row = row0 + ai * HALF + m * 16; const size_t off = (size_t)row * D + col0;
;                 float q = 0.f;
; #pragma unroll
;                 for (int bj = 0; bj < 2; ++bj) {
;                     if (quad >= 0 && (quad & 1) != bj) continue;
;                     const f32x4 v0 = rr[m][bj][0] + acc[ai][bj][m][0] * scale, v1 = rr[m][bj][1] + acc[ai][bj][m][1] * scale;
;                     q += dot4(v0) + dot4(v1);
;                     __builtin_nontemporal_store(v0, (f32x4*)(out + off + bj * HALF)); __builtin_nontemporal_store(v1, (f32x4*)(out + off + bj * HALF + 4));
;                     if (An) { const f32x4 a0 = v0 * gv[bj][0], a1 = v1 * gv[bj][1]; u32x4 w; w.x = pk2(a0[0], a0[1]); w.y = pk2(a0[2], a0[3]); w.z = pk2(a1[0], a1[1]); w.w = pk2(a1[2], a1[3]);
;                         *(u32x4*)(An + off + bj * HALF) = w; }
;                 }
; __device__ __forceinline__ void ph_res_fix(int ph) {
;     ...
;                 for (int n = 0; n < 2; ++n) if (a * 2 + b == quad) acc[a][b][m][n] = s[m * 2 + n];
.LBB0_1125:
	s_or_b64 exec, exec, s[34:35]
	s_waitcnt lgkmcnt(0)
	v_lshlrev_b64 v[64:65], 11, v[120:121]
	v_lshl_add_u64 v[72:73], v[64:65], 0, v[92:93]
	v_mov_b32_e32 v70, 0
	s_and_b64 vcc, exec, s[12:13]
	v_lshl_add_u64 v[66:67], v[64:65], 2, v[98:99]
	v_lshl_add_u64 v[64:65], v[72:73], 1, s[20:21]
	s_cbranch_vccnz .LBB0_1127
	v_cndmask_b32_e64 v71, 0, v97, s[14:15]
	v_cndmask_b32_e64 v70, 0, v96, s[14:15]
	v_cndmask_b32_e64 v75, 0, v103, s[14:15]
	v_cndmask_b32_e64 v74, 0, v102, s[14:15]
	v_cndmask_b32_e64 v73, 0, v95, s[14:15]
	v_cndmask_b32_e64 v72, 0, v94, s[14:15]
	v_cndmask_b32_e64 v77, 0, v101, s[14:15]
	v_cndmask_b32_e64 v76, 0, v100, s[14:15]
	v_pk_add_f32 v[60:61], v[60:61], v[70:71]
	v_pk_add_f32 v[56:57], v[56:57], v[74:75]
	v_pk_add_f32 v[62:63], v[62:63], v[72:73]
	v_pk_add_f32 v[58:59], v[58:59], v[76:77]
	v_mov_b32_e32 v72, v61
	v_mov_b32_e32 v73, v57
	v_mov_b32_e32 v70, v60
	v_mov_b32_e32 v71, v56
	v_pk_mul_f32 v[72:73], v[72:73], v[72:73]
	v_mov_b32_e32 v74, v63
	v_mov_b32_e32 v75, v59
	v_pk_fma_f32 v[70:71], v[70:71], v[70:71], v[72:73]
	v_mov_b32_e32 v72, v62
	v_mov_b32_e32 v73, v58
	v_pk_mul_f32 v[74:75], v[74:75], v[74:75]
	global_store_dwordx4 v[66:67], v[60:63], off
	global_store_dwordx4 v[66:67], v[56:59], off offset:16
	v_pk_fma_f32 v[72:73], v[72:73], v[72:73], v[74:75]
	v_pk_mul_f32 v[62:63], v[14:15], v[62:63]
	v_pk_add_f32 v[70:71], v[70:71], v[72:73]
	v_pk_mul_f32 v[72:73], v[10:11], v[58:59]
	v_add_f32_e32 v70, v70, v71
	v_pk_mul_f32 v[58:59], v[8:9], v[56:57]
	v_pk_mul_f32 v[60:61], v[12:13], v[60:61]
	s_nop 0
	v_cvt_pk_bf16_f32 v56, v60, v61
	v_cvt_pk_bf16_f32 v57, v62, v63
	v_cvt_pk_bf16_f32 v58, v58, v59
	v_cvt_pk_bf16_f32 v59, v72, v73
	global_store_dwordx4 v[64:65], v[56:59], off

; __device__ __forceinline__ unsigned pk2(float lo, float hi) { unsigned r; asm volatile("v_cvt_pk_bf16_f32 %0, %1, %2" : "=v"(r) : "v"(lo), "v"(hi)); return r; }
; __device__ __forceinline__ float dot4(f32x4 v) { return (v[0] * v[0] + v[1] * v[1]) + (v[2] * v[2] + v[3] * v[3]); }
;     __device__ __forceinline__ void operator()(const f32x4 (&acc)[2][2][4][2], const Unit& u, int wr, int wc, int fr, int fq) const {
;     ...
;                 const int row = row0 + ai * HALF + m * 16; const size_t off = (size_t)row * D + col0;
;                 float q = 0.f;
; #pragma unroll
;                 for (int bj = 0; bj < 2; ++bj) {
;                     if (quad >= 0 && (quad & 1) != bj) continue;
;                     const f32x4 v0 = rr[m][bj][0] + acc[ai][bj][m][0] * scale, v1 = rr[m][bj][1] + acc[ai][bj][m][1] * scale;
;                     q += dot4(v0) + dot4(v1);
;                     __builtin_nontemporal_store(v0, (f32x4*)(out + off + bj * HALF)); __builtin_nontemporal_store(v1, (f32x4*)(out + off + bj * HALF + 4));
;                     if (An) { const f32x4 a0 = v0 * gv[bj][0], a1 = v1 * gv[bj][1]; u32x4 w; w.x = pk2(a0[0], a0[1]); w.y = pk2(a0[2], a0[3]); w.z = pk2(a1[0], a1[1]); w.w = pk2(a1[2], a1[3]);
;                         *(u32x4*)(An + off + bj * HALF) = w; }
;                 }
; __device__ __forceinline__ void ph_res_fix(int ph) {
;     ...
;                 for (int n = 0; n < 2; ++n) if (a * 2 + b == quad) acc[a][b][m][n] = s[m * 2 + n];
.LBB0_1131:
	s_or_b64 exec, exec, s[34:35]
	s_waitcnt lgkmcnt(0)
	v_lshlrev_b64 v[48:49], 11, v[118:119]
	v_lshl_add_u64 v[54:55], v[48:49], 0, v[92:93]
	v_mov_b32_e32 v52, 0
	s_and_b64 vcc, exec, s[12:13]
	v_lshl_add_u64 v[50:51], v[48:49], 2, v[98:99]
	v_lshl_add_u64 v[48:49], v[54:55], 1, s[20:21]
	s_cbranch_vccnz .LBB0_1133
	v_cndmask_b32_e64 v53, 0, v87, s[14:15]
	v_cndmask_b32_e64 v52, 0, v86, s[14:15]
	v_cndmask_b32_e64 v57, 0, v107, s[14:15]
	v_cndmask_b32_e64 v56, 0, v106, s[14:15]
	v_cndmask_b32_e64 v55, 0, v85, s[14:15]
	v_cndmask_b32_e64 v54, 0, v84, s[14:15]
	v_cndmask_b32_e64 v59, 0, v105, s[14:15]
	v_cndmask_b32_e64 v58, 0, v104, s[14:15]
	v_pk_add_f32 v[44:45], v[44:45], v[52:53]
	v_pk_add_f32 v[40:41], v[40:41], v[56:57]
	v_pk_add_f32 v[46:47], v[46:47], v[54:55]
	v_pk_add_f32 v[42:43], v[42:43], v[58:59]
	v_mov_b32_e32 v54, v45
	v_mov_b32_e32 v55, v41
	v_mov_b32_e32 v52, v44
	v_mov_b32_e32 v53, v40
	v_pk_mul_f32 v[54:55], v[54:55], v[54:55]
	v_mov_b32_e32 v56, v47
	v_mov_b32_e32 v57, v43
	v_pk_fma_f32 v[52:53], v[52:53], v[52:53], v[54:55]
	v_mov_b32_e32 v54, v46
	v_mov_b32_e32 v55, v42
	v_pk_mul_f32 v[56:57], v[56:57], v[56:57]
	global_store_dwordx4 v[50:51], v[44:47], off
	global_store_dwordx4 v[50:51], v[40:43], off offset:16
	v_pk_fma_f32 v[54:55], v[54:55], v[54:55], v[56:57]
	v_pk_mul_f32 v[46:47], v[14:15], v[46:47]
	v_pk_add_f32 v[52:53], v[52:53], v[54:55]
	v_pk_mul_f32 v[54:55], v[10:11], v[42:43]
	v_add_f32_e32 v52, v52, v53
	v_pk_mul_f32 v[42:43], v[8:9], v[40:41]
	v_pk_mul_f32 v[44:45], v[12:13], v[44:45]
	s_nop 0
	v_cvt_pk_bf16_f32 v40, v44, v45
	v_cvt_pk_bf16_f32 v41, v46, v47
	v_cvt_pk_bf16_f32 v42, v42, v43
	v_cvt_pk_bf16_f32 v43, v54, v55
	global_store_dwordx4 v[48:49], v[40:43], off

; __device__ __forceinline__ unsigned pk2(float lo, float hi) { unsigned r; asm volatile("v_cvt_pk_bf16_f32 %0, %1, %2" : "=v"(r) : "v"(lo), "v"(hi)); return r; }
; __device__ __forceinline__ float dot4(f32x4 v) { return (v[0] * v[0] + v[1] * v[1]) + (v[2] * v[2] + v[3] * v[3]); }
;     __device__ __forceinline__ void operator()(const f32x4 (&acc)[2][2][4][2], const Unit& u, int wr, int wc, int fr, int fq) const {
;     ...
;                 const int row = row0 + ai * HALF + m * 16; const size_t off = (size_t)row * D + col0;
;                 float q = 0.f;
; #pragma unroll
;                 for (int bj = 0; bj < 2; ++bj) {
;                     if (quad >= 0 && (quad & 1) != bj) continue;
;                     const f32x4 v0 = rr[m][bj][0] + acc[ai][bj][m][0] * scale, v1 = rr[m][bj][1] + acc[ai][bj][m][1] * scale;
;                     q += dot4(v0) + dot4(v1);
;                     __builtin_nontemporal_store(v0, (f32x4*)(out + off + bj * HALF)); __builtin_nontemporal_store(v1, (f32x4*)(out + off + bj * HALF + 4));
;                     if (An) { const f32x4 a0 = v0 * gv[bj][0], a1 = v1 * gv[bj][1]; u32x4 w; w.x = pk2(a0[0], a0[1]); w.y = pk2(a0[2], a0[3]); w.z = pk2(a1[0], a1[1]); w.w = pk2(a1[2], a1[3]);
;                         *(u32x4*)(An + off + bj * HALF) = w; }
;                 }
; __device__ __forceinline__ void ph_res_fix(int ph) {
;     ...
;                 for (int n = 0; n < 2; ++n) if (a * 2 + b == quad) acc[a][b][m][n] = s[m * 2 + n];
.LBB0_1137:
	s_or_b64 exec, exec, s[34:35]
	s_waitcnt lgkmcnt(0)
	v_lshlrev_b64 v[32:33], 11, v[116:117]
	v_lshl_add_u64 v[38:39], v[32:33], 0, v[92:93]
	v_mov_b32_e32 v36, 0
	s_and_b64 vcc, exec, s[12:13]
	v_lshl_add_u64 v[34:35], v[32:33], 2, v[98:99]
	v_lshl_add_u64 v[32:33], v[38:39], 1, s[20:21]
	s_cbranch_vccnz .LBB0_1139
	v_cndmask_b32_e64 v37, 0, v83, s[14:15]
	v_cndmask_b32_e64 v36, 0, v82, s[14:15]
	v_cndmask_b32_e64 v41, 0, v91, s[14:15]
	v_cndmask_b32_e64 v40, 0, v90, s[14:15]
	v_cndmask_b32_e64 v39, 0, v81, s[14:15]
	v_cndmask_b32_e64 v38, 0, v80, s[14:15]
	v_cndmask_b32_e64 v43, 0, v89, s[14:15]
	v_cndmask_b32_e64 v42, 0, v88, s[14:15]
	v_pk_add_f32 v[28:29], v[28:29], v[36:37]
	v_pk_add_f32 v[24:25], v[24:25], v[40:41]
	v_pk_add_f32 v[30:31], v[30:31], v[38:39]
	v_pk_add_f32 v[26:27], v[26:27], v[42:43]
	v_mov_b32_e32 v38, v29
	v_mov_b32_e32 v39, v25
	v_mov_b32_e32 v36, v28
	v_mov_b32_e32 v37, v24
	v_pk_mul_f32 v[38:39], v[38:39], v[38:39]
	v_mov_b32_e32 v40, v31
	v_mov_b32_e32 v41, v27
	v_pk_fma_f32 v[36:37], v[36:37], v[36:37], v[38:39]
	v_mov_b32_e32 v38, v30
	v_mov_b32_e32 v39, v26
	v_pk_mul_f32 v[40:41], v[40:41], v[40:41]
	global_store_dwordx4 v[34:35], v[28:31], off
	global_store_dwordx4 v[34:35], v[24:27], off offset:16
	v_pk_fma_f32 v[38:39], v[38:39], v[38:39], v[40:41]
	v_pk_mul_f32 v[14:15], v[14:15], v[30:31]
	v_pk_add_f32 v[36:37], v[36:37], v[38:39]
	v_pk_mul_f32 v[26:27], v[10:11], v[26:27]
	v_add_f32_e32 v36, v36, v37
	v_pk_mul_f32 v[10:11], v[8:9], v[24:25]
	v_pk_mul_f32 v[12:13], v[12:13], v[28:29]
	s_nop 0
	v_cvt_pk_bf16_f32 v8, v12, v13
	v_cvt_pk_bf16_f32 v9, v14, v15
	v_cvt_pk_bf16_f32 v10, v10, v11
	v_cvt_pk_bf16_f32 v11, v26, v27
	global_store_dwordx4 v[32:33], v[8:11], off
.LBB0_1139:
	s_and_b64 vcc, exec, s[10:11]
	s_cbranch_vccnz .LBB0_1141
	v_cndmask_b32_e64 v9, 0, v83, s[16:17]
	v_cndmask_b32_e64 v8, 0, v82, s[16:17]
	v_cndmask_b32_e64 v13, 0, v91, s[16:17]
	v_cndmask_b32_e64 v12, 0, v90, s[16:17]
	v_cndmask_b32_e64 v11, 0, v81, s[16:17]
	v_cndmask_b32_e64 v10, 0, v80, s[16:17]
	v_cndmask_b32_e64 v15, 0, v89, s[16:17]
	v_cndmask_b32_e64 v14, 0, v88, s[16:17]
	v_pk_add_f32 v[8:9], v[20:21], v[8:9]
	v_pk_add_f32 v[12:13], v[16:17], v[12:13]
	v_pk_add_f32 v[10:11], v[22:23], v[10:11]
	v_pk_add_f32 v[14:15], v[18:19], v[14:15]
	v_mov_b32_e32 v18, v9
	v_mov_b32_e32 v19, v13
	v_mov_b32_e32 v16, v8
	v_mov_b32_e32 v17, v12
	v_pk_mul_f32 v[18:19], v[18:19], v[18:19]
	v_mov_b32_e32 v20, v11
	v_mov_b32_e32 v21, v15
	v_pk_fma_f32 v[16:17], v[16:17], v[16:17], v[18:19]
	v_mov_b32_e32 v18, v10
	v_mov_b32_e32 v19, v14
	v_pk_mul_f32 v[20:21], v[20:21], v[20:21]
	global_store_dwordx4 v[34:35], v[8:11], off offset:512
	global_store_dwordx4 v[34:35], v[12:15], off offset:528
	v_pk_fma_f32 v[18:19], v[18:19], v[18:19], v[20:21]
	v_pk_mul_f32 v[4:5], v[4:5], v[8:9]
	v_pk_add_f32 v[16:17], v[16:17], v[18:19]
	v_pk_mul_f32 v[8:9], v[2:3], v[14:15]
	v_add_f32_e32 v16, v16, v17
	v_add_f32_e32 v36, v36, v16
	v_pk_mul_f32 v[2:3], v[0:1], v[12:13]
	v_pk_mul_f32 v[6:7], v[6:7], v[10:11]
	v_cvt_pk_bf16_f32 v0, v4, v5
	s_nop 0
	v_cvt_pk_bf16_f32 v1, v6, v7
	v_cvt_pk_bf16_f32 v2, v2, v3
	v_cvt_pk_bf16_f32 v3, v8, v9
	global_store_dwordx4 v[32:33], v[0:3], off offset:256
